# v4: +pipelined sample-state streaming loop (8 loads in flight), batched even scan loads, DPP wave reductions in row_pass
# speedup vs baseline: 1.0319x; 1.0179x over previous
; __device__ __forceinline__ unsigned pk2(float lo, float hi) { return pg8::cvt_pk_bf16(lo, hi); }
; __device__ __forceinline__ float wave_sum(float v) {
; #pragma unroll
;     for (int o = 1; o < 64; o <<= 1) v += __shfl_xor(v, o);
;     return v;
; }
; __device__ __forceinline__ void row_pass(const Params& p, int mode, float coef, const float* nw, int nsplit) {
;     ...
;             float q = 0.f;
; #pragma unroll
;             for (int j = 0; j < 4; ++j) q += (fv[j][0] * fv[j][0] + fv[j][1] * fv[j][1]) + (fv[j][2] * fv[j][2] + fv[j][3] * fv[j][3]);
;             q = wave_sum(q);
;             const float rstd = rsqrtf(q * (1.0f / D) + EPS) * coef; const f32x4* W4 = (const f32x4*)nw;
; #pragma unroll
;             for (int j = 0; j < 4; ++j) { const f32x4 xv = (f32x4){bf2f(xw[j].x & 0xffffu), bf2f(xw[j].x >> 16), bf2f(xw[j].y & 0xffffu), bf2f(xw[j].y >> 16)};
;                 v[j] = xv + fv[j] * W4[64 * j + lane] * rstd; }
;         }
;         if (mode == 2) { f32x4* X4 = (f32x4*)(p.out + (size_t)r * D);
; #pragma unroll
;             for (int j = 0; j < 4; ++j) X4[64 * j + lane] = v[j];
;         } else {
;             float s = 0.f;
; #pragma unroll
;             for (int j = 0; j < 4; ++j) s += (v[j][0] * v[j][0] + v[j][1] * v[j][1]) + (v[j][2] * v[j][2] + v[j][3] * v[j][3]);
;             s = wave_sum(s);
; #pragma unroll
;             for (int j = 0; j < 4; ++j) { u32x2 w; w.x = pk2(v[j][0], v[j][1]); w.y = pk2(v[j][2], v[j][3]); B2[64 * j + lane] = w; }
;             if (lane == 0) RS[r] = rsqrtf(s * (1.0f / D) + EPS);
.LBB0_457:
	s_or_b64 exec, exec, s[18:19]
	global_load_dwordx4 v[56:59], v[24:25], off
	global_load_dwordx4 v[60:63], v[24:25], off offset:1024
	s_waitcnt lgkmcnt(0)
	v_xor_b32_e32 v18, 1, v164
	v_cmp_lt_i32_e32 vcc, v18, v165
	v_pk_mul_f32 v[50:51], v[6:7], v[6:7]
	v_pk_mul_f32 v[52:53], v[4:5], v[4:5]
	v_cndmask_b32_e32 v76, v164, v18, vcc
	global_load_dwordx4 v[64:67], v[24:25], off offset:2048
	global_load_dwordx4 v[18:21], v[24:25], off offset:3072
	v_pk_mul_f32 v[54:55], v[2:3], v[2:3]
	v_pk_mul_f32 v[68:69], v[0:1], v[0:1]
	v_mul_f32_e32 v16, v8, v8
	v_pk_mov_b32 v[72:73], v[68:69], v[54:55] op_sel:[1,0]
	v_mov_b32_e32 v69, v55
	v_pk_mov_b32 v[54:55], v[52:53], v[50:51] op_sel:[1,0]
	v_mov_b32_e32 v53, v51
	v_mul_f32_e32 v70, v10, v10
	v_pk_add_f32 v[68:69], v[72:73], v[68:69]
	v_pk_add_f32 v[52:53], v[54:55], v[52:53]
	v_pk_fma_f32 v[74:75], v[8:9], v[8:9], v[16:17] op_sel_hi:[1,1,0]
	v_pk_fma_f32 v[70:71], v[10:11], v[10:11], v[70:71] op_sel_hi:[1,1,0]
	v_pk_add_f32 v[54:55], v[68:69], v[68:69] op_sel_hi:[0,1]
	v_pk_add_f32 v[52:53], v[52:53], v[52:53] op_sel_hi:[0,1]
	v_mul_f32_e32 v74, v12, v12
	v_mul_f32_e32 v70, v13, v13
	v_mul_f32_e32 v54, v14, v14
	v_mul_f32_e32 v52, v15, v15
	v_pk_add_f32 v[68:69], v[74:75], v[70:71]
	v_pk_add_f32 v[52:53], v[54:55], v[52:53]
	v_lshlrev_b32_e32 v50, 2, v76
	v_pk_add_f32 v[52:53], v[68:69], v[52:53]
	v_xor_b32_e32 v51, 2, v164
	v_add_f32_e32 v16, v52, v53
	s_nop 1
	v_add_f32_dpp v16, v16, v16 quad_perm:[1,0,3,2] row_mask:0xf bank_mask:0xf
	s_waitcnt vmcnt(6)
	v_lshlrev_b32_e32 v70, 16, v42
	v_add_f32_dpp v16, v16, v16 quad_perm:[2,3,0,1] row_mask:0xf bank_mask:0xf
	v_lshlrev_b32_e32 v68, 16, v44
	s_mov_b64 s[18:19], -1
	v_add_f32_dpp v16, v16, v16 row_ror:4 row_mask:0xf bank_mask:0xf
	v_and_b32_e32 v69, 0xffff0000, v44
	v_lshlrev_b32_e32 v44, 16, v45
	v_add_f32_dpp v16, v16, v16 row_ror:8 row_mask:0xf bank_mask:0xf
	v_and_b32_e32 v45, 0xffff0000, v45
	s_nop 0
	v_add_f32_dpp v16, v16, v16 row_bcast:15 row_mask:0xa bank_mask:0xf
	s_nop 1
	v_add_f32_dpp v16, v16, v16 row_bcast:31 row_mask:0xc bank_mask:0xf
	s_nop 0
	v_readlane_b32 s20, v16, 63
	v_mov_b32_e32 v71, 0x358637bd
	s_nop 0
	v_mov_b32_e32 v16, s20
	v_fmamk_f32 v16, v16, 0x3a800000, v71
	v_mul_f32_e32 v71, 0x4b800000, v16
	v_cmp_gt_f32_e32 vcc, s33, v16
	s_waitcnt vmcnt(2)
	v_pk_mul_f32 v[6:7], v[6:7], v[62:63]
	v_pk_mul_f32 v[2:3], v[2:3], v[58:59]
	v_cndmask_b32_e32 v16, v16, v71, vcc
	v_rsq_f32_e32 v16, v16
	v_and_b32_e32 v71, 0xffff0000, v42
	v_lshlrev_b32_e32 v42, 16, v43
	v_and_b32_e32 v43, 0xffff0000, v43
	v_mul_f32_e32 v72, 0x45800000, v16
	v_cndmask_b32_e32 v16, v16, v72, vcc
	v_mul_f32_e32 v16, 0.5, v16
	v_pk_fma_f32 v[6:7], v[6:7], v[16:17], v[42:43] op_sel_hi:[1,0,1]
	v_lshlrev_b32_e32 v42, 16, v40
	v_and_b32_e32 v43, 0xffff0000, v40
	v_lshlrev_b32_e32 v40, 16, v41
	v_and_b32_e32 v41, 0xffff0000, v41
	s_waitcnt vmcnt(1)
	v_pk_mul_f32 v[10:11], v[10:11], v[66:67]
	v_pk_mul_f32 v[0:1], v[0:1], v[56:57]
	v_pk_mul_f32 v[4:5], v[4:5], v[60:61]
	v_pk_mul_f32 v[8:9], v[8:9], v[64:65]
	v_pk_fma_f32 v[10:11], v[10:11], v[16:17], v[40:41] op_sel_hi:[1,0,1]
	v_lshlrev_b32_e32 v40, 16, v38
	v_and_b32_e32 v41, 0xffff0000, v38
	v_lshlrev_b32_e32 v38, 16, v39
	v_and_b32_e32 v39, 0xffff0000, v39
	s_waitcnt vmcnt(0)
	v_pk_mul_f32 v[14:15], v[14:15], v[20:21]
	v_pk_mul_f32 v[12:13], v[12:13], v[18:19]
	v_pk_fma_f32 v[2:3], v[2:3], v[16:17], v[44:45] op_sel_hi:[1,0,1]
	v_pk_fma_f32 v[0:1], v[0:1], v[16:17], v[68:69] op_sel_hi:[1,0,1]
	v_pk_fma_f32 v[4:5], v[4:5], v[16:17], v[70:71] op_sel_hi:[1,0,1]
	v_pk_fma_f32 v[8:9], v[8:9], v[16:17], v[42:43] op_sel_hi:[1,0,1]
	v_pk_fma_f32 v[14:15], v[14:15], v[16:17], v[38:39] op_sel_hi:[1,0,1]
	v_pk_fma_f32 v[12:13], v[12:13], v[16:17], v[40:41] op_sel_hi:[1,0,1]
	s_andn2_b64 vcc, exec, s[8:9]
	s_cbranch_vccnz .LBB0_461
	v_mul_f32_e32 v16, v1, v1
	v_mul_f32_e32 v18, v3, v3
	v_fmac_f32_e32 v16, v0, v0
	v_fmac_f32_e32 v18, v2, v2
	v_add_f32_e32 v16, v16, v18
	v_mul_f32_e32 v18, v5, v5
	v_mul_f32_e32 v19, v7, v7
	v_fmac_f32_e32 v18, v4, v4
	v_fmac_f32_e32 v19, v6, v6
	v_add_f32_e32 v18, v18, v19
	v_add_f32_e32 v16, v16, v18
	v_mul_f32_e32 v18, v9, v9
	v_mul_f32_e32 v19, v11, v11
	v_fmac_f32_e32 v18, v8, v8
	v_fmac_f32_e32 v19, v10, v10
	v_add_f32_e32 v18, v18, v19
	v_add_f32_e32 v16, v18, v16
	v_mul_f32_e32 v18, v13, v13
	v_mul_f32_e32 v19, v15, v15
	v_fmac_f32_e32 v18, v12, v12
	v_fmac_f32_e32 v19, v14, v14
	v_add_f32_e32 v18, v18, v19
	v_add_f32_e32 v16, v18, v16
	s_nop 1
	v_add_f32_dpp v16, v16, v16 quad_perm:[1,0,3,2] row_mask:0xf bank_mask:0xf
	v_cvt_pk_bf16_f32 v18, v0, v1
	v_cvt_pk_bf16_f32 v19, v2, v3
	v_add_f32_dpp v16, v16, v16 quad_perm:[2,3,0,1] row_mask:0xf bank_mask:0xf
	global_store_dwordx2 v[34:35], v[18:19], off
	s_nop 0
	v_add_f32_dpp v16, v16, v16 row_ror:4 row_mask:0xf bank_mask:0xf
	s_nop 1
	v_add_f32_dpp v16, v16, v16 row_ror:8 row_mask:0xf bank_mask:0xf
	s_nop 1
	v_add_f32_dpp v16, v16, v16 row_bcast:15 row_mask:0xa bank_mask:0xf
	s_nop 1
	v_add_f32_dpp v16, v16, v16 row_bcast:31 row_mask:0xc bank_mask:0xf
	s_nop 0
	v_readlane_b32 s20, v16, 63
	v_cvt_pk_bf16_f32 v20, v4, v5
	v_cvt_pk_bf16_f32 v21, v6, v7
	global_store_dwordx2 v[34:35], v[20:21], off offset:512
	v_cvt_pk_bf16_f32 v20, v8, v9
	v_cvt_pk_bf16_f32 v21, v10, v11
	global_store_dwordx2 v[34:35], v[20:21], off offset:1024
	v_cvt_pk_bf16_f32 v20, v12, v13
	v_cvt_pk_bf16_f32 v21, v14, v15
	global_store_dwordx2 v[34:35], v[20:21], off offset:1536
	s_and_saveexec_b64 s[18:19], s[12:13]
	s_cbranch_execz .LBB0_460
	v_mov_b32_e32 v16, s20
	v_mov_b32_e32 v18, 0x358637bd
	v_fmamk_f32 v16, v16, 0x3a800000, v18
	v_mul_f32_e32 v18, 0x4b800000, v16
	v_cmp_gt_f32_e32 vcc, s33, v16
	v_readlane_b32 s20, v252, 39
	v_readlane_b32 s21, v252, 40
	v_cndmask_b32_e32 v16, v16, v18, vcc
	v_rsq_f32_e32 v16, v16
	s_nop 0
	v_mul_f32_e32 v18, 0x45800000, v16
	v_cndmask_b32_e32 v16, v16, v18, vcc
	v_lshl_add_u64 v[18:19], v[32:33], 2, s[20:21]
	global_store_dword v[18:19], v16, off

; #define LAS __attribute__((address_space(3)))
; template <int TY> __device__ __forceinline__ void sample_item(const Params& p, ldsp lds, int item) {
;     ...
;     const int e4 = tid % E4, dg = tid / E4;
;     f32x4 v[8], o[8];
; #pragma unroll
;     for (int t = 0; t < 8; ++t) { v[t] = *(const LAS f32x4*)(Vs + t * DV + e4 * 4); o[t] = (f32x4){0.f, 0.f, 0.f, 0.f}; }
;     const float* S0 = (TY == 0 ? p.in[2] : (TY == 1 ? p.in[3] : p.in[4])) + (size_t)item * DK * DV;
;     float* S1 = p.out + (TY == 0 ? OUT_GLA_S : (TY == 1 ? OUT_HGRN_S : OUT_RET_S)) + (size_t)item * DK * DV;
; #pragma unroll 8
;     for (int d = dg; d < DK; d += NG) { const f32x4 s0 = __builtin_nontemporal_load((const f32x4*)(S0 + (size_t)d * DV + e4 * 4));
;         const f32x4 qa = *(const LAS f32x4*)(QK + d * 16), qb = *(const LAS f32x4*)(QK + d * 16 + 4), ka = *(const LAS f32x4*)(QK + d * 16 + 8), kb = *(const LAS f32x4*)(QK + d * 16 + 12);
;         const float dc = DECs[d];
;         o[0] += s0 * qa[0]; o[1] += s0 * qa[1]; o[2] += s0 * qa[2]; o[3] += s0 * qa[3]; o[4] += s0 * qb[0]; o[5] += s0 * qb[1]; o[6] += s0 * qb[2]; o[7] += s0 * qb[3];
;         f32x4 sn = s0 * dc; sn += v[0] * ka[0]; sn += v[1] * ka[1]; sn += v[2] * ka[2]; sn += v[3] * ka[3]; sn += v[4] * kb[0]; sn += v[5] * kb[1]; sn += v[6] * kb[2]; sn += v[7] * kb[3];
;         __builtin_nontemporal_store(sn, (f32x4*)(S1 + (size_t)d * DV + e4 * 4)); }
.LBB0_705:
	s_or_b64 exec, exec, s[8:9]
	v_cmp_lt_u32_e32 vcc, 27, v74
	s_and_saveexec_b64 s[8:9], vcc
	s_cbranch_execz .LBB0_709
	v_lshlrev_b64 v[18:19], 2, v[70:71]
	s_add_i32 s10, 0, 0xa000
	v_lshl_add_u32 v16, v98, 2, s10
	v_lshl_add_u32 v118, v98, 6, 0
	v_lshl_add_u32 v104, v98, 11, v18
	v_add_u32_e32 v105, 0x2000, v104
	v_add_u32_e32 v106, 0x4000, v104
	v_add_u32_e32 v107, 0x6000, v104
	v_add_u32_e32 v108, 0x8000, v104
	v_add_u32_e32 v109, 0xa000, v104
	v_add_u32_e32 v110, 0xc000, v104
	v_add_u32_e32 v111, 0xe000, v104
	s_mov_b64 s[10:11], 0
	global_load_dwordx4 v[72:75], v104, s[12:13] nt
	global_load_dwordx4 v[76:79], v105, s[12:13] nt
	global_load_dwordx4 v[80:83], v106, s[12:13] nt
	global_load_dwordx4 v[84:87], v107, s[12:13] nt
	global_load_dwordx4 v[88:91], v108, s[12:13] nt
	global_load_dwordx4 v[92:95], v109, s[12:13] nt
	global_load_dwordx4 v[96:99], v110, s[12:13] nt
	global_load_dwordx4 v[100:103], v111, s[12:13] nt
	ds_read_b128 v[120:123], v118
	ds_read_b128 v[124:127], v118 offset:16
	ds_read_b128 v[128:131], v118 offset:32
	ds_read_b128 v[132:135], v118 offset:48
	ds_read_b32 v136, v16 offset:0
	s_waitcnt vmcnt(7) lgkmcnt(3)
	v_pk_fma_f32 v[64:65], v[72:73], v[120:121], v[64:65] op_sel_hi:[1,0,1]
	v_pk_fma_f32 v[66:67], v[74:75], v[120:121], v[66:67] op_sel_hi:[1,0,1]
	v_pk_fma_f32 v[60:61], v[72:73], v[120:121], v[60:61] op_sel:[0,1,0]
	v_pk_fma_f32 v[62:63], v[74:75], v[120:121], v[62:63] op_sel:[0,1,0]
	v_pk_fma_f32 v[56:57], v[72:73], v[122:123], v[56:57] op_sel_hi:[1,0,1]
	v_pk_fma_f32 v[58:59], v[74:75], v[122:123], v[58:59] op_sel_hi:[1,0,1]
	v_pk_fma_f32 v[52:53], v[72:73], v[122:123], v[52:53] op_sel:[0,1,0]
	v_pk_fma_f32 v[54:55], v[74:75], v[122:123], v[54:55] op_sel:[0,1,0]
	v_pk_fma_f32 v[48:49], v[72:73], v[124:125], v[48:49] op_sel_hi:[1,0,1]
	v_pk_fma_f32 v[50:51], v[74:75], v[124:125], v[50:51] op_sel_hi:[1,0,1]
	v_pk_fma_f32 v[40:41], v[72:73], v[124:125], v[40:41] op_sel:[0,1,0]
	v_pk_fma_f32 v[42:43], v[74:75], v[124:125], v[42:43] op_sel:[0,1,0]
	v_pk_fma_f32 v[36:37], v[72:73], v[126:127], v[36:37] op_sel_hi:[1,0,1]
	v_pk_fma_f32 v[38:39], v[74:75], v[126:127], v[38:39] op_sel_hi:[1,0,1]
	v_pk_fma_f32 v[44:45], v[72:73], v[126:127], v[44:45] op_sel:[0,1,0]
	v_pk_fma_f32 v[46:47], v[74:75], v[126:127], v[46:47] op_sel:[0,1,0]
	ds_read_b128 v[120:123], v118 offset:256
	ds_read_b128 v[124:127], v118 offset:272
	s_waitcnt lgkmcnt(2)
	v_pk_mul_f32 v[72:73], v[72:73], v[136:137] op_sel_hi:[1,0]
	v_pk_mul_f32 v[74:75], v[74:75], v[136:137] op_sel_hi:[1,0]
	v_pk_fma_f32 v[72:73], v[0:1], v[128:129], v[72:73] op_sel_hi:[1,0,1]
	v_pk_fma_f32 v[74:75], v[2:3], v[128:129], v[74:75] op_sel_hi:[1,0,1]
	v_pk_fma_f32 v[72:73], v[4:5], v[128:129], v[72:73] op_sel:[0,1,0]
	v_pk_fma_f32 v[74:75], v[6:7], v[128:129], v[74:75] op_sel:[0,1,0]
	v_pk_fma_f32 v[72:73], v[8:9], v[130:131], v[72:73] op_sel_hi:[1,0,1]
	v_pk_fma_f32 v[74:75], v[10:11], v[130:131], v[74:75] op_sel_hi:[1,0,1]
	v_pk_fma_f32 v[72:73], v[12:13], v[130:131], v[72:73] op_sel:[0,1,0]
	v_pk_fma_f32 v[74:75], v[14:15], v[130:131], v[74:75] op_sel:[0,1,0]
	v_pk_fma_f32 v[72:73], v[20:21], v[132:133], v[72:73] op_sel_hi:[1,0,1]
	v_pk_fma_f32 v[74:75], v[22:23], v[132:133], v[74:75] op_sel_hi:[1,0,1]
	v_pk_fma_f32 v[72:73], v[24:25], v[132:133], v[72:73] op_sel:[0,1,0]
	v_pk_fma_f32 v[74:75], v[26:27], v[132:133], v[74:75] op_sel:[0,1,0]
	v_pk_fma_f32 v[72:73], v[28:29], v[134:135], v[72:73] op_sel_hi:[1,0,1]
	v_pk_fma_f32 v[74:75], v[30:31], v[134:135], v[74:75] op_sel_hi:[1,0,1]
	v_pk_fma_f32 v[72:73], v[32:33], v[134:135], v[72:73] op_sel:[0,1,0]
	v_pk_fma_f32 v[74:75], v[34:35], v[134:135], v[74:75] op_sel:[0,1,0]
	global_store_dwordx4 v104, v[72:75], s[14:15] nt
	v_add_u32_e32 v104, 0x10000, v104
	global_load_dwordx4 v[72:75], v104, s[12:13] nt
	ds_read_b128 v[128:131], v118 offset:288
	ds_read_b128 v[132:135], v118 offset:304
	ds_read_b32 v136, v16 offset:16
	s_waitcnt vmcnt(8) lgkmcnt(3)
	v_pk_fma_f32 v[64:65], v[76:77], v[120:121], v[64:65] op_sel_hi:[1,0,1]
	v_pk_fma_f32 v[66:67], v[78:79], v[120:121], v[66:67] op_sel_hi:[1,0,1]
	v_pk_fma_f32 v[60:61], v[76:77], v[120:121], v[60:61] op_sel:[0,1,0]
	v_pk_fma_f32 v[62:63], v[78:79], v[120:121], v[62:63] op_sel:[0,1,0]
	v_pk_fma_f32 v[56:57], v[76:77], v[122:123], v[56:57] op_sel_hi:[1,0,1]
	v_pk_fma_f32 v[58:59], v[78:79], v[122:123], v[58:59] op_sel_hi:[1,0,1]
	v_pk_fma_f32 v[52:53], v[76:77], v[122:123], v[52:53] op_sel:[0,1,0]
	v_pk_fma_f32 v[54:55], v[78:79], v[122:123], v[54:55] op_sel:[0,1,0]
	v_pk_fma_f32 v[48:49], v[76:77], v[124:125], v[48:49] op_sel_hi:[1,0,1]
	v_pk_fma_f32 v[50:51], v[78:79], v[124:125], v[50:51] op_sel_hi:[1,0,1]
	v_pk_fma_f32 v[40:41], v[76:77], v[124:125], v[40:41] op_sel:[0,1,0]
	v_pk_fma_f32 v[42:43], v[78:79], v[124:125], v[42:43] op_sel:[0,1,0]
	v_pk_fma_f32 v[36:37], v[76:77], v[126:127], v[36:37] op_sel_hi:[1,0,1]
	v_pk_fma_f32 v[38:39], v[78:79], v[126:127], v[38:39] op_sel_hi:[1,0,1]
	v_pk_fma_f32 v[44:45], v[76:77], v[126:127], v[44:45] op_sel:[0,1,0]
	v_pk_fma_f32 v[46:47], v[78:79], v[126:127], v[46:47] op_sel:[0,1,0]
	ds_read_b128 v[120:123], v118 offset:512
	ds_read_b128 v[124:127], v118 offset:528
	s_waitcnt lgkmcnt(2)
; #define LAS __attribute__((address_space(3)))
; template <int TY> __device__ __forceinline__ void sample_item(const Params& p, ldsp lds, int item) {
;     ...
; #pragma unroll 8
;     for (int d = dg; d < DK; d += NG) { const f32x4 s0 = __builtin_nontemporal_load((const f32x4*)(S0 + (size_t)d * DV + e4 * 4));
;         const f32x4 qa = *(const LAS f32x4*)(QK + d * 16), qb = *(const LAS f32x4*)(QK + d * 16 + 4), ka = *(const LAS f32x4*)(QK + d * 16 + 8), kb = *(const LAS f32x4*)(QK + d * 16 + 12);
;         const float dc = DECs[d];
;         o[0] += s0 * qa[0]; o[1] += s0 * qa[1]; o[2] += s0 * qa[2]; o[3] += s0 * qa[3]; o[4] += s0 * qb[0]; o[5] += s0 * qb[1]; o[6] += s0 * qb[2]; o[7] += s0 * qb[3];
;         f32x4 sn = s0 * dc; sn += v[0] * ka[0]; sn += v[1] * ka[1]; sn += v[2] * ka[2]; sn += v[3] * ka[3]; sn += v[4] * kb[0]; sn += v[5] * kb[1]; sn += v[6] * kb[2]; sn += v[7] * kb[3];
;         __builtin_nontemporal_store(sn, (f32x4*)(S1 + (size_t)d * DV + e4 * 4)); }
	v_pk_mul_f32 v[76:77], v[76:77], v[136:137] op_sel_hi:[1,0]
	v_pk_mul_f32 v[78:79], v[78:79], v[136:137] op_sel_hi:[1,0]
	v_pk_fma_f32 v[76:77], v[0:1], v[128:129], v[76:77] op_sel_hi:[1,0,1]
	v_pk_fma_f32 v[78:79], v[2:3], v[128:129], v[78:79] op_sel_hi:[1,0,1]
	v_pk_fma_f32 v[76:77], v[4:5], v[128:129], v[76:77] op_sel:[0,1,0]
	v_pk_fma_f32 v[78:79], v[6:7], v[128:129], v[78:79] op_sel:[0,1,0]
	v_pk_fma_f32 v[76:77], v[8:9], v[130:131], v[76:77] op_sel_hi:[1,0,1]
	v_pk_fma_f32 v[78:79], v[10:11], v[130:131], v[78:79] op_sel_hi:[1,0,1]
	v_pk_fma_f32 v[76:77], v[12:13], v[130:131], v[76:77] op_sel:[0,1,0]
	v_pk_fma_f32 v[78:79], v[14:15], v[130:131], v[78:79] op_sel:[0,1,0]
	v_pk_fma_f32 v[76:77], v[20:21], v[132:133], v[76:77] op_sel_hi:[1,0,1]
	v_pk_fma_f32 v[78:79], v[22:23], v[132:133], v[78:79] op_sel_hi:[1,0,1]
	v_pk_fma_f32 v[76:77], v[24:25], v[132:133], v[76:77] op_sel:[0,1,0]
	v_pk_fma_f32 v[78:79], v[26:27], v[132:133], v[78:79] op_sel:[0,1,0]
	v_pk_fma_f32 v[76:77], v[28:29], v[134:135], v[76:77] op_sel_hi:[1,0,1]
	v_pk_fma_f32 v[78:79], v[30:31], v[134:135], v[78:79] op_sel_hi:[1,0,1]
	v_pk_fma_f32 v[76:77], v[32:33], v[134:135], v[76:77] op_sel:[0,1,0]
	v_pk_fma_f32 v[78:79], v[34:35], v[134:135], v[78:79] op_sel:[0,1,0]
	global_store_dwordx4 v105, v[76:79], s[14:15] nt
	v_add_u32_e32 v105, 0x10000, v105
	global_load_dwordx4 v[76:79], v105, s[12:13] nt
	ds_read_b128 v[128:131], v118 offset:544
	ds_read_b128 v[132:135], v118 offset:560
	ds_read_b32 v136, v16 offset:32
	s_waitcnt vmcnt(9) lgkmcnt(3)
	v_pk_fma_f32 v[64:65], v[80:81], v[120:121], v[64:65] op_sel_hi:[1,0,1]
	v_pk_fma_f32 v[66:67], v[82:83], v[120:121], v[66:67] op_sel_hi:[1,0,1]
	v_pk_fma_f32 v[60:61], v[80:81], v[120:121], v[60:61] op_sel:[0,1,0]
	v_pk_fma_f32 v[62:63], v[82:83], v[120:121], v[62:63] op_sel:[0,1,0]
	v_pk_fma_f32 v[56:57], v[80:81], v[122:123], v[56:57] op_sel_hi:[1,0,1]
	v_pk_fma_f32 v[58:59], v[82:83], v[122:123], v[58:59] op_sel_hi:[1,0,1]
	v_pk_fma_f32 v[52:53], v[80:81], v[122:123], v[52:53] op_sel:[0,1,0]
	v_pk_fma_f32 v[54:55], v[82:83], v[122:123], v[54:55] op_sel:[0,1,0]
	v_pk_fma_f32 v[48:49], v[80:81], v[124:125], v[48:49] op_sel_hi:[1,0,1]
	v_pk_fma_f32 v[50:51], v[82:83], v[124:125], v[50:51] op_sel_hi:[1,0,1]
	v_pk_fma_f32 v[40:41], v[80:81], v[124:125], v[40:41] op_sel:[0,1,0]
	v_pk_fma_f32 v[42:43], v[82:83], v[124:125], v[42:43] op_sel:[0,1,0]
	v_pk_fma_f32 v[36:37], v[80:81], v[126:127], v[36:37] op_sel_hi:[1,0,1]
	v_pk_fma_f32 v[38:39], v[82:83], v[126:127], v[38:39] op_sel_hi:[1,0,1]
	v_pk_fma_f32 v[44:45], v[80:81], v[126:127], v[44:45] op_sel:[0,1,0]
	v_pk_fma_f32 v[46:47], v[82:83], v[126:127], v[46:47] op_sel:[0,1,0]
	ds_read_b128 v[120:123], v118 offset:768
	ds_read_b128 v[124:127], v118 offset:784
	s_waitcnt lgkmcnt(2)
	v_pk_mul_f32 v[80:81], v[80:81], v[136:137] op_sel_hi:[1,0]
	v_pk_mul_f32 v[82:83], v[82:83], v[136:137] op_sel_hi:[1,0]
	v_pk_fma_f32 v[80:81], v[0:1], v[128:129], v[80:81] op_sel_hi:[1,0,1]
	v_pk_fma_f32 v[82:83], v[2:3], v[128:129], v[82:83] op_sel_hi:[1,0,1]
	v_pk_fma_f32 v[80:81], v[4:5], v[128:129], v[80:81] op_sel:[0,1,0]
	v_pk_fma_f32 v[82:83], v[6:7], v[128:129], v[82:83] op_sel:[0,1,0]
	v_pk_fma_f32 v[80:81], v[8:9], v[130:131], v[80:81] op_sel_hi:[1,0,1]
	v_pk_fma_f32 v[82:83], v[10:11], v[130:131], v[82:83] op_sel_hi:[1,0,1]
	v_pk_fma_f32 v[80:81], v[12:13], v[130:131], v[80:81] op_sel:[0,1,0]
	v_pk_fma_f32 v[82:83], v[14:15], v[130:131], v[82:83] op_sel:[0,1,0]
	v_pk_fma_f32 v[80:81], v[20:21], v[132:133], v[80:81] op_sel_hi:[1,0,1]
	v_pk_fma_f32 v[82:83], v[22:23], v[132:133], v[82:83] op_sel_hi:[1,0,1]
	v_pk_fma_f32 v[80:81], v[24:25], v[132:133], v[80:81] op_sel:[0,1,0]
	v_pk_fma_f32 v[82:83], v[26:27], v[132:133], v[82:83] op_sel:[0,1,0]
	v_pk_fma_f32 v[80:81], v[28:29], v[134:135], v[80:81] op_sel_hi:[1,0,1]
	v_pk_fma_f32 v[82:83], v[30:31], v[134:135], v[82:83] op_sel_hi:[1,0,1]
	v_pk_fma_f32 v[80:81], v[32:33], v[134:135], v[80:81] op_sel:[0,1,0]
	v_pk_fma_f32 v[82:83], v[34:35], v[134:135], v[82:83] op_sel:[0,1,0]
	global_store_dwordx4 v106, v[80:83], s[14:15] nt
	v_add_u32_e32 v106, 0x10000, v106
	global_load_dwordx4 v[80:83], v106, s[12:13] nt
	ds_read_b128 v[128:131], v118 offset:800
	ds_read_b128 v[132:135], v118 offset:816
	ds_read_b32 v136, v16 offset:48
	s_waitcnt vmcnt(10) lgkmcnt(3)
	v_pk_fma_f32 v[64:65], v[84:85], v[120:121], v[64:65] op_sel_hi:[1,0,1]
	v_pk_fma_f32 v[66:67], v[86:87], v[120:121], v[66:67] op_sel_hi:[1,0,1]
	v_pk_fma_f32 v[60:61], v[84:85], v[120:121], v[60:61] op_sel:[0,1,0]
	v_pk_fma_f32 v[62:63], v[86:87], v[120:121], v[62:63] op_sel:[0,1,0]
	v_pk_fma_f32 v[56:57], v[84:85], v[122:123], v[56:57] op_sel_hi:[1,0,1]
	v_pk_fma_f32 v[58:59], v[86:87], v[122:123], v[58:59] op_sel_hi:[1,0,1]
	v_pk_fma_f32 v[52:53], v[84:85], v[122:123], v[52:53] op_sel:[0,1,0]
	v_pk_fma_f32 v[54:55], v[86:87], v[122:123], v[54:55] op_sel:[0,1,0]
	v_pk_fma_f32 v[48:49], v[84:85], v[124:125], v[48:49] op_sel_hi:[1,0,1]
	v_pk_fma_f32 v[50:51], v[86:87], v[124:125], v[50:51] op_sel_hi:[1,0,1]
	v_pk_fma_f32 v[40:41], v[84:85], v[124:125], v[40:41] op_sel:[0,1,0]
	v_pk_fma_f32 v[42:43], v[86:87], v[124:125], v[42:43] op_sel:[0,1,0]
	v_pk_fma_f32 v[36:37], v[84:85], v[126:127], v[36:37] op_sel_hi:[1,0,1]
	v_pk_fma_f32 v[38:39], v[86:87], v[126:127], v[38:39] op_sel_hi:[1,0,1]
	v_pk_fma_f32 v[44:45], v[84:85], v[126:127], v[44:45] op_sel:[0,1,0]
	v_pk_fma_f32 v[46:47], v[86:87], v[126:127], v[46:47] op_sel:[0,1,0]
	ds_read_b128 v[120:123], v118 offset:1024
	ds_read_b128 v[124:127], v118 offset:1040
	s_waitcnt lgkmcnt(2)
; #define LAS __attribute__((address_space(3)))
; template <int TY> __device__ __forceinline__ void sample_item(const Params& p, ldsp lds, int item) {
;     ...
; #pragma unroll 8
;     for (int d = dg; d < DK; d += NG) { const f32x4 s0 = __builtin_nontemporal_load((const f32x4*)(S0 + (size_t)d * DV + e4 * 4));
;         const f32x4 qa = *(const LAS f32x4*)(QK + d * 16), qb = *(const LAS f32x4*)(QK + d * 16 + 4), ka = *(const LAS f32x4*)(QK + d * 16 + 8), kb = *(const LAS f32x4*)(QK + d * 16 + 12);
;         const float dc = DECs[d];
;         o[0] += s0 * qa[0]; o[1] += s0 * qa[1]; o[2] += s0 * qa[2]; o[3] += s0 * qa[3]; o[4] += s0 * qb[0]; o[5] += s0 * qb[1]; o[6] += s0 * qb[2]; o[7] += s0 * qb[3];
;         f32x4 sn = s0 * dc; sn += v[0] * ka[0]; sn += v[1] * ka[1]; sn += v[2] * ka[2]; sn += v[3] * ka[3]; sn += v[4] * kb[0]; sn += v[5] * kb[1]; sn += v[6] * kb[2]; sn += v[7] * kb[3];
;         __builtin_nontemporal_store(sn, (f32x4*)(S1 + (size_t)d * DV + e4 * 4)); }
	v_pk_mul_f32 v[84:85], v[84:85], v[136:137] op_sel_hi:[1,0]
	v_pk_mul_f32 v[86:87], v[86:87], v[136:137] op_sel_hi:[1,0]
	v_pk_fma_f32 v[84:85], v[0:1], v[128:129], v[84:85] op_sel_hi:[1,0,1]
	v_pk_fma_f32 v[86:87], v[2:3], v[128:129], v[86:87] op_sel_hi:[1,0,1]
	v_pk_fma_f32 v[84:85], v[4:5], v[128:129], v[84:85] op_sel:[0,1,0]
	v_pk_fma_f32 v[86:87], v[6:7], v[128:129], v[86:87] op_sel:[0,1,0]
	v_pk_fma_f32 v[84:85], v[8:9], v[130:131], v[84:85] op_sel_hi:[1,0,1]
	v_pk_fma_f32 v[86:87], v[10:11], v[130:131], v[86:87] op_sel_hi:[1,0,1]
	v_pk_fma_f32 v[84:85], v[12:13], v[130:131], v[84:85] op_sel:[0,1,0]
	v_pk_fma_f32 v[86:87], v[14:15], v[130:131], v[86:87] op_sel:[0,1,0]
	v_pk_fma_f32 v[84:85], v[20:21], v[132:133], v[84:85] op_sel_hi:[1,0,1]
	v_pk_fma_f32 v[86:87], v[22:23], v[132:133], v[86:87] op_sel_hi:[1,0,1]
	v_pk_fma_f32 v[84:85], v[24:25], v[132:133], v[84:85] op_sel:[0,1,0]
	v_pk_fma_f32 v[86:87], v[26:27], v[132:133], v[86:87] op_sel:[0,1,0]
	v_pk_fma_f32 v[84:85], v[28:29], v[134:135], v[84:85] op_sel_hi:[1,0,1]
	v_pk_fma_f32 v[86:87], v[30:31], v[134:135], v[86:87] op_sel_hi:[1,0,1]
	v_pk_fma_f32 v[84:85], v[32:33], v[134:135], v[84:85] op_sel:[0,1,0]
	v_pk_fma_f32 v[86:87], v[34:35], v[134:135], v[86:87] op_sel:[0,1,0]
	global_store_dwordx4 v107, v[84:87], s[14:15] nt
	v_add_u32_e32 v107, 0x10000, v107
	global_load_dwordx4 v[84:87], v107, s[12:13] nt
	ds_read_b128 v[128:131], v118 offset:1056
	ds_read_b128 v[132:135], v118 offset:1072
	ds_read_b32 v136, v16 offset:64
	s_waitcnt vmcnt(11) lgkmcnt(3)
	v_pk_fma_f32 v[64:65], v[88:89], v[120:121], v[64:65] op_sel_hi:[1,0,1]
	v_pk_fma_f32 v[66:67], v[90:91], v[120:121], v[66:67] op_sel_hi:[1,0,1]
	v_pk_fma_f32 v[60:61], v[88:89], v[120:121], v[60:61] op_sel:[0,1,0]
	v_pk_fma_f32 v[62:63], v[90:91], v[120:121], v[62:63] op_sel:[0,1,0]
	v_pk_fma_f32 v[56:57], v[88:89], v[122:123], v[56:57] op_sel_hi:[1,0,1]
	v_pk_fma_f32 v[58:59], v[90:91], v[122:123], v[58:59] op_sel_hi:[1,0,1]
	v_pk_fma_f32 v[52:53], v[88:89], v[122:123], v[52:53] op_sel:[0,1,0]
	v_pk_fma_f32 v[54:55], v[90:91], v[122:123], v[54:55] op_sel:[0,1,0]
	v_pk_fma_f32 v[48:49], v[88:89], v[124:125], v[48:49] op_sel_hi:[1,0,1]
	v_pk_fma_f32 v[50:51], v[90:91], v[124:125], v[50:51] op_sel_hi:[1,0,1]
	v_pk_fma_f32 v[40:41], v[88:89], v[124:125], v[40:41] op_sel:[0,1,0]
	v_pk_fma_f32 v[42:43], v[90:91], v[124:125], v[42:43] op_sel:[0,1,0]
	v_pk_fma_f32 v[36:37], v[88:89], v[126:127], v[36:37] op_sel_hi:[1,0,1]
	v_pk_fma_f32 v[38:39], v[90:91], v[126:127], v[38:39] op_sel_hi:[1,0,1]
	v_pk_fma_f32 v[44:45], v[88:89], v[126:127], v[44:45] op_sel:[0,1,0]
	v_pk_fma_f32 v[46:47], v[90:91], v[126:127], v[46:47] op_sel:[0,1,0]
	ds_read_b128 v[120:123], v118 offset:1280
	ds_read_b128 v[124:127], v118 offset:1296
	s_waitcnt lgkmcnt(2)
	v_pk_mul_f32 v[88:89], v[88:89], v[136:137] op_sel_hi:[1,0]
	v_pk_mul_f32 v[90:91], v[90:91], v[136:137] op_sel_hi:[1,0]
	v_pk_fma_f32 v[88:89], v[0:1], v[128:129], v[88:89] op_sel_hi:[1,0,1]
	v_pk_fma_f32 v[90:91], v[2:3], v[128:129], v[90:91] op_sel_hi:[1,0,1]
	v_pk_fma_f32 v[88:89], v[4:5], v[128:129], v[88:89] op_sel:[0,1,0]
	v_pk_fma_f32 v[90:91], v[6:7], v[128:129], v[90:91] op_sel:[0,1,0]
	v_pk_fma_f32 v[88:89], v[8:9], v[130:131], v[88:89] op_sel_hi:[1,0,1]
	v_pk_fma_f32 v[90:91], v[10:11], v[130:131], v[90:91] op_sel_hi:[1,0,1]
	v_pk_fma_f32 v[88:89], v[12:13], v[130:131], v[88:89] op_sel:[0,1,0]
	v_pk_fma_f32 v[90:91], v[14:15], v[130:131], v[90:91] op_sel:[0,1,0]
	v_pk_fma_f32 v[88:89], v[20:21], v[132:133], v[88:89] op_sel_hi:[1,0,1]
	v_pk_fma_f32 v[90:91], v[22:23], v[132:133], v[90:91] op_sel_hi:[1,0,1]
	v_pk_fma_f32 v[88:89], v[24:25], v[132:133], v[88:89] op_sel:[0,1,0]
	v_pk_fma_f32 v[90:91], v[26:27], v[132:133], v[90:91] op_sel:[0,1,0]
	v_pk_fma_f32 v[88:89], v[28:29], v[134:135], v[88:89] op_sel_hi:[1,0,1]
	v_pk_fma_f32 v[90:91], v[30:31], v[134:135], v[90:91] op_sel_hi:[1,0,1]
	v_pk_fma_f32 v[88:89], v[32:33], v[134:135], v[88:89] op_sel:[0,1,0]
	v_pk_fma_f32 v[90:91], v[34:35], v[134:135], v[90:91] op_sel:[0,1,0]
	global_store_dwordx4 v108, v[88:91], s[14:15] nt
	v_add_u32_e32 v108, 0x10000, v108
	global_load_dwordx4 v[88:91], v108, s[12:13] nt
	ds_read_b128 v[128:131], v118 offset:1312
	ds_read_b128 v[132:135], v118 offset:1328
	ds_read_b32 v136, v16 offset:80
	s_waitcnt vmcnt(12) lgkmcnt(3)
	v_pk_fma_f32 v[64:65], v[92:93], v[120:121], v[64:65] op_sel_hi:[1,0,1]
	v_pk_fma_f32 v[66:67], v[94:95], v[120:121], v[66:67] op_sel_hi:[1,0,1]
	v_pk_fma_f32 v[60:61], v[92:93], v[120:121], v[60:61] op_sel:[0,1,0]
	v_pk_fma_f32 v[62:63], v[94:95], v[120:121], v[62:63] op_sel:[0,1,0]
	v_pk_fma_f32 v[56:57], v[92:93], v[122:123], v[56:57] op_sel_hi:[1,0,1]
	v_pk_fma_f32 v[58:59], v[94:95], v[122:123], v[58:59] op_sel_hi:[1,0,1]
	v_pk_fma_f32 v[52:53], v[92:93], v[122:123], v[52:53] op_sel:[0,1,0]
	v_pk_fma_f32 v[54:55], v[94:95], v[122:123], v[54:55] op_sel:[0,1,0]
	v_pk_fma_f32 v[48:49], v[92:93], v[124:125], v[48:49] op_sel_hi:[1,0,1]
	v_pk_fma_f32 v[50:51], v[94:95], v[124:125], v[50:51] op_sel_hi:[1,0,1]
	v_pk_fma_f32 v[40:41], v[92:93], v[124:125], v[40:41] op_sel:[0,1,0]
	v_pk_fma_f32 v[42:43], v[94:95], v[124:125], v[42:43] op_sel:[0,1,0]
	v_pk_fma_f32 v[36:37], v[92:93], v[126:127], v[36:37] op_sel_hi:[1,0,1]
	v_pk_fma_f32 v[38:39], v[94:95], v[126:127], v[38:39] op_sel_hi:[1,0,1]
	v_pk_fma_f32 v[44:45], v[92:93], v[126:127], v[44:45] op_sel:[0,1,0]
	v_pk_fma_f32 v[46:47], v[94:95], v[126:127], v[46:47] op_sel:[0,1,0]
	ds_read_b128 v[120:123], v118 offset:1536
	ds_read_b128 v[124:127], v118 offset:1552
	s_waitcnt lgkmcnt(2)
; #define LAS __attribute__((address_space(3)))
; template <int TY> __device__ __forceinline__ void sample_item(const Params& p, ldsp lds, int item) {
;     ...
; #pragma unroll 8
;     for (int d = dg; d < DK; d += NG) { const f32x4 s0 = __builtin_nontemporal_load((const f32x4*)(S0 + (size_t)d * DV + e4 * 4));
;         const f32x4 qa = *(const LAS f32x4*)(QK + d * 16), qb = *(const LAS f32x4*)(QK + d * 16 + 4), ka = *(const LAS f32x4*)(QK + d * 16 + 8), kb = *(const LAS f32x4*)(QK + d * 16 + 12);
;         const float dc = DECs[d];
;         o[0] += s0 * qa[0]; o[1] += s0 * qa[1]; o[2] += s0 * qa[2]; o[3] += s0 * qa[3]; o[4] += s0 * qb[0]; o[5] += s0 * qb[1]; o[6] += s0 * qb[2]; o[7] += s0 * qb[3];
;         f32x4 sn = s0 * dc; sn += v[0] * ka[0]; sn += v[1] * ka[1]; sn += v[2] * ka[2]; sn += v[3] * ka[3]; sn += v[4] * kb[0]; sn += v[5] * kb[1]; sn += v[6] * kb[2]; sn += v[7] * kb[3];
;         __builtin_nontemporal_store(sn, (f32x4*)(S1 + (size_t)d * DV + e4 * 4)); }
	v_pk_mul_f32 v[92:93], v[92:93], v[136:137] op_sel_hi:[1,0]
	v_pk_mul_f32 v[94:95], v[94:95], v[136:137] op_sel_hi:[1,0]
	v_pk_fma_f32 v[92:93], v[0:1], v[128:129], v[92:93] op_sel_hi:[1,0,1]
	v_pk_fma_f32 v[94:95], v[2:3], v[128:129], v[94:95] op_sel_hi:[1,0,1]
	v_pk_fma_f32 v[92:93], v[4:5], v[128:129], v[92:93] op_sel:[0,1,0]
	v_pk_fma_f32 v[94:95], v[6:7], v[128:129], v[94:95] op_sel:[0,1,0]
	v_pk_fma_f32 v[92:93], v[8:9], v[130:131], v[92:93] op_sel_hi:[1,0,1]
	v_pk_fma_f32 v[94:95], v[10:11], v[130:131], v[94:95] op_sel_hi:[1,0,1]
	v_pk_fma_f32 v[92:93], v[12:13], v[130:131], v[92:93] op_sel:[0,1,0]
	v_pk_fma_f32 v[94:95], v[14:15], v[130:131], v[94:95] op_sel:[0,1,0]
	v_pk_fma_f32 v[92:93], v[20:21], v[132:133], v[92:93] op_sel_hi:[1,0,1]
	v_pk_fma_f32 v[94:95], v[22:23], v[132:133], v[94:95] op_sel_hi:[1,0,1]
	v_pk_fma_f32 v[92:93], v[24:25], v[132:133], v[92:93] op_sel:[0,1,0]
	v_pk_fma_f32 v[94:95], v[26:27], v[132:133], v[94:95] op_sel:[0,1,0]
	v_pk_fma_f32 v[92:93], v[28:29], v[134:135], v[92:93] op_sel_hi:[1,0,1]
	v_pk_fma_f32 v[94:95], v[30:31], v[134:135], v[94:95] op_sel_hi:[1,0,1]
	v_pk_fma_f32 v[92:93], v[32:33], v[134:135], v[92:93] op_sel:[0,1,0]
	v_pk_fma_f32 v[94:95], v[34:35], v[134:135], v[94:95] op_sel:[0,1,0]
	global_store_dwordx4 v109, v[92:95], s[14:15] nt
	v_add_u32_e32 v109, 0x10000, v109
	global_load_dwordx4 v[92:95], v109, s[12:13] nt
	ds_read_b128 v[128:131], v118 offset:1568
	ds_read_b128 v[132:135], v118 offset:1584
	ds_read_b32 v136, v16 offset:96
	s_waitcnt vmcnt(13) lgkmcnt(3)
	v_pk_fma_f32 v[64:65], v[96:97], v[120:121], v[64:65] op_sel_hi:[1,0,1]
	v_pk_fma_f32 v[66:67], v[98:99], v[120:121], v[66:67] op_sel_hi:[1,0,1]
	v_pk_fma_f32 v[60:61], v[96:97], v[120:121], v[60:61] op_sel:[0,1,0]
	v_pk_fma_f32 v[62:63], v[98:99], v[120:121], v[62:63] op_sel:[0,1,0]
	v_pk_fma_f32 v[56:57], v[96:97], v[122:123], v[56:57] op_sel_hi:[1,0,1]
	v_pk_fma_f32 v[58:59], v[98:99], v[122:123], v[58:59] op_sel_hi:[1,0,1]
	v_pk_fma_f32 v[52:53], v[96:97], v[122:123], v[52:53] op_sel:[0,1,0]
	v_pk_fma_f32 v[54:55], v[98:99], v[122:123], v[54:55] op_sel:[0,1,0]
	v_pk_fma_f32 v[48:49], v[96:97], v[124:125], v[48:49] op_sel_hi:[1,0,1]
	v_pk_fma_f32 v[50:51], v[98:99], v[124:125], v[50:51] op_sel_hi:[1,0,1]
	v_pk_fma_f32 v[40:41], v[96:97], v[124:125], v[40:41] op_sel:[0,1,0]
	v_pk_fma_f32 v[42:43], v[98:99], v[124:125], v[42:43] op_sel:[0,1,0]
	v_pk_fma_f32 v[36:37], v[96:97], v[126:127], v[36:37] op_sel_hi:[1,0,1]
	v_pk_fma_f32 v[38:39], v[98:99], v[126:127], v[38:39] op_sel_hi:[1,0,1]
	v_pk_fma_f32 v[44:45], v[96:97], v[126:127], v[44:45] op_sel:[0,1,0]
	v_pk_fma_f32 v[46:47], v[98:99], v[126:127], v[46:47] op_sel:[0,1,0]
	ds_read_b128 v[120:123], v118 offset:1792
	ds_read_b128 v[124:127], v118 offset:1808
	s_waitcnt lgkmcnt(2)
	v_pk_mul_f32 v[96:97], v[96:97], v[136:137] op_sel_hi:[1,0]
	v_pk_mul_f32 v[98:99], v[98:99], v[136:137] op_sel_hi:[1,0]
	v_pk_fma_f32 v[96:97], v[0:1], v[128:129], v[96:97] op_sel_hi:[1,0,1]
	v_pk_fma_f32 v[98:99], v[2:3], v[128:129], v[98:99] op_sel_hi:[1,0,1]
	v_pk_fma_f32 v[96:97], v[4:5], v[128:129], v[96:97] op_sel:[0,1,0]
	v_pk_fma_f32 v[98:99], v[6:7], v[128:129], v[98:99] op_sel:[0,1,0]
	v_pk_fma_f32 v[96:97], v[8:9], v[130:131], v[96:97] op_sel_hi:[1,0,1]
	v_pk_fma_f32 v[98:99], v[10:11], v[130:131], v[98:99] op_sel_hi:[1,0,1]
	v_pk_fma_f32 v[96:97], v[12:13], v[130:131], v[96:97] op_sel:[0,1,0]
	v_pk_fma_f32 v[98:99], v[14:15], v[130:131], v[98:99] op_sel:[0,1,0]
	v_pk_fma_f32 v[96:97], v[20:21], v[132:133], v[96:97] op_sel_hi:[1,0,1]
	v_pk_fma_f32 v[98:99], v[22:23], v[132:133], v[98:99] op_sel_hi:[1,0,1]
	v_pk_fma_f32 v[96:97], v[24:25], v[132:133], v[96:97] op_sel:[0,1,0]
	v_pk_fma_f32 v[98:99], v[26:27], v[132:133], v[98:99] op_sel:[0,1,0]
	v_pk_fma_f32 v[96:97], v[28:29], v[134:135], v[96:97] op_sel_hi:[1,0,1]
	v_pk_fma_f32 v[98:99], v[30:31], v[134:135], v[98:99] op_sel_hi:[1,0,1]
	v_pk_fma_f32 v[96:97], v[32:33], v[134:135], v[96:97] op_sel:[0,1,0]
	v_pk_fma_f32 v[98:99], v[34:35], v[134:135], v[98:99] op_sel:[0,1,0]
	global_store_dwordx4 v110, v[96:99], s[14:15] nt
	v_add_u32_e32 v110, 0x10000, v110
	global_load_dwordx4 v[96:99], v110, s[12:13] nt
	ds_read_b128 v[128:131], v118 offset:1824
	ds_read_b128 v[132:135], v118 offset:1840
	ds_read_b32 v136, v16 offset:112
	s_waitcnt vmcnt(14) lgkmcnt(3)
	v_pk_fma_f32 v[64:65], v[100:101], v[120:121], v[64:65] op_sel_hi:[1,0,1]
	v_pk_fma_f32 v[66:67], v[102:103], v[120:121], v[66:67] op_sel_hi:[1,0,1]
	v_pk_fma_f32 v[60:61], v[100:101], v[120:121], v[60:61] op_sel:[0,1,0]
	v_pk_fma_f32 v[62:63], v[102:103], v[120:121], v[62:63] op_sel:[0,1,0]
	v_pk_fma_f32 v[56:57], v[100:101], v[122:123], v[56:57] op_sel_hi:[1,0,1]
	v_pk_fma_f32 v[58:59], v[102:103], v[122:123], v[58:59] op_sel_hi:[1,0,1]
	v_pk_fma_f32 v[52:53], v[100:101], v[122:123], v[52:53] op_sel:[0,1,0]
	v_pk_fma_f32 v[54:55], v[102:103], v[122:123], v[54:55] op_sel:[0,1,0]
	v_pk_fma_f32 v[48:49], v[100:101], v[124:125], v[48:49] op_sel_hi:[1,0,1]
	v_pk_fma_f32 v[50:51], v[102:103], v[124:125], v[50:51] op_sel_hi:[1,0,1]
	v_pk_fma_f32 v[40:41], v[100:101], v[124:125], v[40:41] op_sel:[0,1,0]
	v_pk_fma_f32 v[42:43], v[102:103], v[124:125], v[42:43] op_sel:[0,1,0]
	v_pk_fma_f32 v[36:37], v[100:101], v[126:127], v[36:37] op_sel_hi:[1,0,1]
	v_pk_fma_f32 v[38:39], v[102:103], v[126:127], v[38:39] op_sel_hi:[1,0,1]
	v_pk_fma_f32 v[44:45], v[100:101], v[126:127], v[44:45] op_sel:[0,1,0]
	v_pk_fma_f32 v[46:47], v[102:103], v[126:127], v[46:47] op_sel:[0,1,0]
	ds_read_b128 v[120:123], v118 offset:2048
	ds_read_b128 v[124:127], v118 offset:2064
	s_waitcnt lgkmcnt(2)
; #define LAS __attribute__((address_space(3)))
; template <int TY> __device__ __forceinline__ void sample_item(const Params& p, ldsp lds, int item) {
;     ...
; #pragma unroll 8
;     for (int d = dg; d < DK; d += NG) { const f32x4 s0 = __builtin_nontemporal_load((const f32x4*)(S0 + (size_t)d * DV + e4 * 4));
;         const f32x4 qa = *(const LAS f32x4*)(QK + d * 16), qb = *(const LAS f32x4*)(QK + d * 16 + 4), ka = *(const LAS f32x4*)(QK + d * 16 + 8), kb = *(const LAS f32x4*)(QK + d * 16 + 12);
;         const float dc = DECs[d];
;         o[0] += s0 * qa[0]; o[1] += s0 * qa[1]; o[2] += s0 * qa[2]; o[3] += s0 * qa[3]; o[4] += s0 * qb[0]; o[5] += s0 * qb[1]; o[6] += s0 * qb[2]; o[7] += s0 * qb[3];
;         f32x4 sn = s0 * dc; sn += v[0] * ka[0]; sn += v[1] * ka[1]; sn += v[2] * ka[2]; sn += v[3] * ka[3]; sn += v[4] * kb[0]; sn += v[5] * kb[1]; sn += v[6] * kb[2]; sn += v[7] * kb[3];
;         __builtin_nontemporal_store(sn, (f32x4*)(S1 + (size_t)d * DV + e4 * 4)); }
	v_pk_mul_f32 v[100:101], v[100:101], v[136:137] op_sel_hi:[1,0]
	v_pk_mul_f32 v[102:103], v[102:103], v[136:137] op_sel_hi:[1,0]
	v_pk_fma_f32 v[100:101], v[0:1], v[128:129], v[100:101] op_sel_hi:[1,0,1]
	v_pk_fma_f32 v[102:103], v[2:3], v[128:129], v[102:103] op_sel_hi:[1,0,1]
	v_pk_fma_f32 v[100:101], v[4:5], v[128:129], v[100:101] op_sel:[0,1,0]
	v_pk_fma_f32 v[102:103], v[6:7], v[128:129], v[102:103] op_sel:[0,1,0]
	v_pk_fma_f32 v[100:101], v[8:9], v[130:131], v[100:101] op_sel_hi:[1,0,1]
	v_pk_fma_f32 v[102:103], v[10:11], v[130:131], v[102:103] op_sel_hi:[1,0,1]
	v_pk_fma_f32 v[100:101], v[12:13], v[130:131], v[100:101] op_sel:[0,1,0]
	v_pk_fma_f32 v[102:103], v[14:15], v[130:131], v[102:103] op_sel:[0,1,0]
	v_pk_fma_f32 v[100:101], v[20:21], v[132:133], v[100:101] op_sel_hi:[1,0,1]
	v_pk_fma_f32 v[102:103], v[22:23], v[132:133], v[102:103] op_sel_hi:[1,0,1]
	v_pk_fma_f32 v[100:101], v[24:25], v[132:133], v[100:101] op_sel:[0,1,0]
	v_pk_fma_f32 v[102:103], v[26:27], v[132:133], v[102:103] op_sel:[0,1,0]
	v_pk_fma_f32 v[100:101], v[28:29], v[134:135], v[100:101] op_sel_hi:[1,0,1]
	v_pk_fma_f32 v[102:103], v[30:31], v[134:135], v[102:103] op_sel_hi:[1,0,1]
	v_pk_fma_f32 v[100:101], v[32:33], v[134:135], v[100:101] op_sel:[0,1,0]
	v_pk_fma_f32 v[102:103], v[34:35], v[134:135], v[102:103] op_sel:[0,1,0]
	global_store_dwordx4 v111, v[100:103], s[14:15] nt
	v_add_u32_e32 v111, 0x10000, v111
	global_load_dwordx4 v[100:103], v111, s[12:13] nt
	v_add_u32_e32 v118, 0x800, v118
	v_add_u32_e32 v16, 0x80, v16
	s_mov_b32 s16, 0
.Lsm2_stream_loop:
	ds_read_b128 v[128:131], v118 offset:32
	ds_read_b128 v[132:135], v118 offset:48
	ds_read_b32 v136, v16 offset:0
	s_waitcnt vmcnt(14) lgkmcnt(3)
	v_pk_fma_f32 v[64:65], v[72:73], v[120:121], v[64:65] op_sel_hi:[1,0,1]
	v_pk_fma_f32 v[66:67], v[74:75], v[120:121], v[66:67] op_sel_hi:[1,0,1]
	v_pk_fma_f32 v[60:61], v[72:73], v[120:121], v[60:61] op_sel:[0,1,0]
	v_pk_fma_f32 v[62:63], v[74:75], v[120:121], v[62:63] op_sel:[0,1,0]
	v_pk_fma_f32 v[56:57], v[72:73], v[122:123], v[56:57] op_sel_hi:[1,0,1]
	v_pk_fma_f32 v[58:59], v[74:75], v[122:123], v[58:59] op_sel_hi:[1,0,1]
	v_pk_fma_f32 v[52:53], v[72:73], v[122:123], v[52:53] op_sel:[0,1,0]
	v_pk_fma_f32 v[54:55], v[74:75], v[122:123], v[54:55] op_sel:[0,1,0]
	v_pk_fma_f32 v[48:49], v[72:73], v[124:125], v[48:49] op_sel_hi:[1,0,1]
	v_pk_fma_f32 v[50:51], v[74:75], v[124:125], v[50:51] op_sel_hi:[1,0,1]
	v_pk_fma_f32 v[40:41], v[72:73], v[124:125], v[40:41] op_sel:[0,1,0]
	v_pk_fma_f32 v[42:43], v[74:75], v[124:125], v[42:43] op_sel:[0,1,0]
	v_pk_fma_f32 v[36:37], v[72:73], v[126:127], v[36:37] op_sel_hi:[1,0,1]
	v_pk_fma_f32 v[38:39], v[74:75], v[126:127], v[38:39] op_sel_hi:[1,0,1]
	v_pk_fma_f32 v[44:45], v[72:73], v[126:127], v[44:45] op_sel:[0,1,0]
	v_pk_fma_f32 v[46:47], v[74:75], v[126:127], v[46:47] op_sel:[0,1,0]
	ds_read_b128 v[120:123], v118 offset:256
	ds_read_b128 v[124:127], v118 offset:272
	s_waitcnt lgkmcnt(2)
	v_pk_mul_f32 v[72:73], v[72:73], v[136:137] op_sel_hi:[1,0]
	v_pk_mul_f32 v[74:75], v[74:75], v[136:137] op_sel_hi:[1,0]
	v_pk_fma_f32 v[72:73], v[0:1], v[128:129], v[72:73] op_sel_hi:[1,0,1]
	v_pk_fma_f32 v[74:75], v[2:3], v[128:129], v[74:75] op_sel_hi:[1,0,1]
	v_pk_fma_f32 v[72:73], v[4:5], v[128:129], v[72:73] op_sel:[0,1,0]
	v_pk_fma_f32 v[74:75], v[6:7], v[128:129], v[74:75] op_sel:[0,1,0]
	v_pk_fma_f32 v[72:73], v[8:9], v[130:131], v[72:73] op_sel_hi:[1,0,1]
	v_pk_fma_f32 v[74:75], v[10:11], v[130:131], v[74:75] op_sel_hi:[1,0,1]
	v_pk_fma_f32 v[72:73], v[12:13], v[130:131], v[72:73] op_sel:[0,1,0]
	v_pk_fma_f32 v[74:75], v[14:15], v[130:131], v[74:75] op_sel:[0,1,0]
	v_pk_fma_f32 v[72:73], v[20:21], v[132:133], v[72:73] op_sel_hi:[1,0,1]
	v_pk_fma_f32 v[74:75], v[22:23], v[132:133], v[74:75] op_sel_hi:[1,0,1]
	v_pk_fma_f32 v[72:73], v[24:25], v[132:133], v[72:73] op_sel:[0,1,0]
	v_pk_fma_f32 v[74:75], v[26:27], v[132:133], v[74:75] op_sel:[0,1,0]
	v_pk_fma_f32 v[72:73], v[28:29], v[134:135], v[72:73] op_sel_hi:[1,0,1]
	v_pk_fma_f32 v[74:75], v[30:31], v[134:135], v[74:75] op_sel_hi:[1,0,1]
	v_pk_fma_f32 v[72:73], v[32:33], v[134:135], v[72:73] op_sel:[0,1,0]
	v_pk_fma_f32 v[74:75], v[34:35], v[134:135], v[74:75] op_sel:[0,1,0]
	global_store_dwordx4 v104, v[72:75], s[14:15] nt
	v_add_u32_e32 v104, 0x10000, v104
	global_load_dwordx4 v[72:75], v104, s[12:13] nt
	ds_read_b128 v[128:131], v118 offset:288
	ds_read_b128 v[132:135], v118 offset:304
	ds_read_b32 v136, v16 offset:16
	s_waitcnt vmcnt(14) lgkmcnt(3)
	v_pk_fma_f32 v[64:65], v[76:77], v[120:121], v[64:65] op_sel_hi:[1,0,1]
	v_pk_fma_f32 v[66:67], v[78:79], v[120:121], v[66:67] op_sel_hi:[1,0,1]
	v_pk_fma_f32 v[60:61], v[76:77], v[120:121], v[60:61] op_sel:[0,1,0]
	v_pk_fma_f32 v[62:63], v[78:79], v[120:121], v[62:63] op_sel:[0,1,0]
	v_pk_fma_f32 v[56:57], v[76:77], v[122:123], v[56:57] op_sel_hi:[1,0,1]
	v_pk_fma_f32 v[58:59], v[78:79], v[122:123], v[58:59] op_sel_hi:[1,0,1]
	v_pk_fma_f32 v[52:53], v[76:77], v[122:123], v[52:53] op_sel:[0,1,0]
	v_pk_fma_f32 v[54:55], v[78:79], v[122:123], v[54:55] op_sel:[0,1,0]
	v_pk_fma_f32 v[48:49], v[76:77], v[124:125], v[48:49] op_sel_hi:[1,0,1]
	v_pk_fma_f32 v[50:51], v[78:79], v[124:125], v[50:51] op_sel_hi:[1,0,1]
	v_pk_fma_f32 v[40:41], v[76:77], v[124:125], v[40:41] op_sel:[0,1,0]
	v_pk_fma_f32 v[42:43], v[78:79], v[124:125], v[42:43] op_sel:[0,1,0]
	v_pk_fma_f32 v[36:37], v[76:77], v[126:127], v[36:37] op_sel_hi:[1,0,1]
	v_pk_fma_f32 v[38:39], v[78:79], v[126:127], v[38:39] op_sel_hi:[1,0,1]
	v_pk_fma_f32 v[44:45], v[76:77], v[126:127], v[44:45] op_sel:[0,1,0]
	v_pk_fma_f32 v[46:47], v[78:79], v[126:127], v[46:47] op_sel:[0,1,0]
	ds_read_b128 v[120:123], v118 offset:512
	ds_read_b128 v[124:127], v118 offset:528
	s_waitcnt lgkmcnt(2)
; #define LAS __attribute__((address_space(3)))
; template <int TY> __device__ __forceinline__ void sample_item(const Params& p, ldsp lds, int item) {
;     ...
; #pragma unroll 8
;     for (int d = dg; d < DK; d += NG) { const f32x4 s0 = __builtin_nontemporal_load((const f32x4*)(S0 + (size_t)d * DV + e4 * 4));
;         const f32x4 qa = *(const LAS f32x4*)(QK + d * 16), qb = *(const LAS f32x4*)(QK + d * 16 + 4), ka = *(const LAS f32x4*)(QK + d * 16 + 8), kb = *(const LAS f32x4*)(QK + d * 16 + 12);
;         const float dc = DECs[d];
;         o[0] += s0 * qa[0]; o[1] += s0 * qa[1]; o[2] += s0 * qa[2]; o[3] += s0 * qa[3]; o[4] += s0 * qb[0]; o[5] += s0 * qb[1]; o[6] += s0 * qb[2]; o[7] += s0 * qb[3];
;         f32x4 sn = s0 * dc; sn += v[0] * ka[0]; sn += v[1] * ka[1]; sn += v[2] * ka[2]; sn += v[3] * ka[3]; sn += v[4] * kb[0]; sn += v[5] * kb[1]; sn += v[6] * kb[2]; sn += v[7] * kb[3];
;         __builtin_nontemporal_store(sn, (f32x4*)(S1 + (size_t)d * DV + e4 * 4)); }
	v_pk_mul_f32 v[76:77], v[76:77], v[136:137] op_sel_hi:[1,0]
	v_pk_mul_f32 v[78:79], v[78:79], v[136:137] op_sel_hi:[1,0]
	v_pk_fma_f32 v[76:77], v[0:1], v[128:129], v[76:77] op_sel_hi:[1,0,1]
	v_pk_fma_f32 v[78:79], v[2:3], v[128:129], v[78:79] op_sel_hi:[1,0,1]
	v_pk_fma_f32 v[76:77], v[4:5], v[128:129], v[76:77] op_sel:[0,1,0]
	v_pk_fma_f32 v[78:79], v[6:7], v[128:129], v[78:79] op_sel:[0,1,0]
	v_pk_fma_f32 v[76:77], v[8:9], v[130:131], v[76:77] op_sel_hi:[1,0,1]
	v_pk_fma_f32 v[78:79], v[10:11], v[130:131], v[78:79] op_sel_hi:[1,0,1]
	v_pk_fma_f32 v[76:77], v[12:13], v[130:131], v[76:77] op_sel:[0,1,0]
	v_pk_fma_f32 v[78:79], v[14:15], v[130:131], v[78:79] op_sel:[0,1,0]
	v_pk_fma_f32 v[76:77], v[20:21], v[132:133], v[76:77] op_sel_hi:[1,0,1]
	v_pk_fma_f32 v[78:79], v[22:23], v[132:133], v[78:79] op_sel_hi:[1,0,1]
	v_pk_fma_f32 v[76:77], v[24:25], v[132:133], v[76:77] op_sel:[0,1,0]
	v_pk_fma_f32 v[78:79], v[26:27], v[132:133], v[78:79] op_sel:[0,1,0]
	v_pk_fma_f32 v[76:77], v[28:29], v[134:135], v[76:77] op_sel_hi:[1,0,1]
	v_pk_fma_f32 v[78:79], v[30:31], v[134:135], v[78:79] op_sel_hi:[1,0,1]
	v_pk_fma_f32 v[76:77], v[32:33], v[134:135], v[76:77] op_sel:[0,1,0]
	v_pk_fma_f32 v[78:79], v[34:35], v[134:135], v[78:79] op_sel:[0,1,0]
	global_store_dwordx4 v105, v[76:79], s[14:15] nt
	v_add_u32_e32 v105, 0x10000, v105
	global_load_dwordx4 v[76:79], v105, s[12:13] nt
	ds_read_b128 v[128:131], v118 offset:544
	ds_read_b128 v[132:135], v118 offset:560
	ds_read_b32 v136, v16 offset:32
	s_waitcnt vmcnt(14) lgkmcnt(3)
	v_pk_fma_f32 v[64:65], v[80:81], v[120:121], v[64:65] op_sel_hi:[1,0,1]
	v_pk_fma_f32 v[66:67], v[82:83], v[120:121], v[66:67] op_sel_hi:[1,0,1]
	v_pk_fma_f32 v[60:61], v[80:81], v[120:121], v[60:61] op_sel:[0,1,0]
	v_pk_fma_f32 v[62:63], v[82:83], v[120:121], v[62:63] op_sel:[0,1,0]
	v_pk_fma_f32 v[56:57], v[80:81], v[122:123], v[56:57] op_sel_hi:[1,0,1]
	v_pk_fma_f32 v[58:59], v[82:83], v[122:123], v[58:59] op_sel_hi:[1,0,1]
	v_pk_fma_f32 v[52:53], v[80:81], v[122:123], v[52:53] op_sel:[0,1,0]
	v_pk_fma_f32 v[54:55], v[82:83], v[122:123], v[54:55] op_sel:[0,1,0]
	v_pk_fma_f32 v[48:49], v[80:81], v[124:125], v[48:49] op_sel_hi:[1,0,1]
	v_pk_fma_f32 v[50:51], v[82:83], v[124:125], v[50:51] op_sel_hi:[1,0,1]
	v_pk_fma_f32 v[40:41], v[80:81], v[124:125], v[40:41] op_sel:[0,1,0]
	v_pk_fma_f32 v[42:43], v[82:83], v[124:125], v[42:43] op_sel:[0,1,0]
	v_pk_fma_f32 v[36:37], v[80:81], v[126:127], v[36:37] op_sel_hi:[1,0,1]
	v_pk_fma_f32 v[38:39], v[82:83], v[126:127], v[38:39] op_sel_hi:[1,0,1]
	v_pk_fma_f32 v[44:45], v[80:81], v[126:127], v[44:45] op_sel:[0,1,0]
	v_pk_fma_f32 v[46:47], v[82:83], v[126:127], v[46:47] op_sel:[0,1,0]
	ds_read_b128 v[120:123], v118 offset:768
	ds_read_b128 v[124:127], v118 offset:784
	s_waitcnt lgkmcnt(2)
	v_pk_mul_f32 v[80:81], v[80:81], v[136:137] op_sel_hi:[1,0]
	v_pk_mul_f32 v[82:83], v[82:83], v[136:137] op_sel_hi:[1,0]
	v_pk_fma_f32 v[80:81], v[0:1], v[128:129], v[80:81] op_sel_hi:[1,0,1]
	v_pk_fma_f32 v[82:83], v[2:3], v[128:129], v[82:83] op_sel_hi:[1,0,1]
	v_pk_fma_f32 v[80:81], v[4:5], v[128:129], v[80:81] op_sel:[0,1,0]
	v_pk_fma_f32 v[82:83], v[6:7], v[128:129], v[82:83] op_sel:[0,1,0]
	v_pk_fma_f32 v[80:81], v[8:9], v[130:131], v[80:81] op_sel_hi:[1,0,1]
	v_pk_fma_f32 v[82:83], v[10:11], v[130:131], v[82:83] op_sel_hi:[1,0,1]
	v_pk_fma_f32 v[80:81], v[12:13], v[130:131], v[80:81] op_sel:[0,1,0]
	v_pk_fma_f32 v[82:83], v[14:15], v[130:131], v[82:83] op_sel:[0,1,0]
	v_pk_fma_f32 v[80:81], v[20:21], v[132:133], v[80:81] op_sel_hi:[1,0,1]
	v_pk_fma_f32 v[82:83], v[22:23], v[132:133], v[82:83] op_sel_hi:[1,0,1]
	v_pk_fma_f32 v[80:81], v[24:25], v[132:133], v[80:81] op_sel:[0,1,0]
	v_pk_fma_f32 v[82:83], v[26:27], v[132:133], v[82:83] op_sel:[0,1,0]
	v_pk_fma_f32 v[80:81], v[28:29], v[134:135], v[80:81] op_sel_hi:[1,0,1]
	v_pk_fma_f32 v[82:83], v[30:31], v[134:135], v[82:83] op_sel_hi:[1,0,1]
	v_pk_fma_f32 v[80:81], v[32:33], v[134:135], v[80:81] op_sel:[0,1,0]
	v_pk_fma_f32 v[82:83], v[34:35], v[134:135], v[82:83] op_sel:[0,1,0]
	global_store_dwordx4 v106, v[80:83], s[14:15] nt
	v_add_u32_e32 v106, 0x10000, v106
	global_load_dwordx4 v[80:83], v106, s[12:13] nt
	ds_read_b128 v[128:131], v118 offset:800
	ds_read_b128 v[132:135], v118 offset:816
	ds_read_b32 v136, v16 offset:48
	s_waitcnt vmcnt(14) lgkmcnt(3)
	v_pk_fma_f32 v[64:65], v[84:85], v[120:121], v[64:65] op_sel_hi:[1,0,1]
	v_pk_fma_f32 v[66:67], v[86:87], v[120:121], v[66:67] op_sel_hi:[1,0,1]
	v_pk_fma_f32 v[60:61], v[84:85], v[120:121], v[60:61] op_sel:[0,1,0]
	v_pk_fma_f32 v[62:63], v[86:87], v[120:121], v[62:63] op_sel:[0,1,0]
	v_pk_fma_f32 v[56:57], v[84:85], v[122:123], v[56:57] op_sel_hi:[1,0,1]
	v_pk_fma_f32 v[58:59], v[86:87], v[122:123], v[58:59] op_sel_hi:[1,0,1]
	v_pk_fma_f32 v[52:53], v[84:85], v[122:123], v[52:53] op_sel:[0,1,0]
	v_pk_fma_f32 v[54:55], v[86:87], v[122:123], v[54:55] op_sel:[0,1,0]
	v_pk_fma_f32 v[48:49], v[84:85], v[124:125], v[48:49] op_sel_hi:[1,0,1]
	v_pk_fma_f32 v[50:51], v[86:87], v[124:125], v[50:51] op_sel_hi:[1,0,1]
	v_pk_fma_f32 v[40:41], v[84:85], v[124:125], v[40:41] op_sel:[0,1,0]
	v_pk_fma_f32 v[42:43], v[86:87], v[124:125], v[42:43] op_sel:[0,1,0]
	v_pk_fma_f32 v[36:37], v[84:85], v[126:127], v[36:37] op_sel_hi:[1,0,1]
	v_pk_fma_f32 v[38:39], v[86:87], v[126:127], v[38:39] op_sel_hi:[1,0,1]
	v_pk_fma_f32 v[44:45], v[84:85], v[126:127], v[44:45] op_sel:[0,1,0]
	v_pk_fma_f32 v[46:47], v[86:87], v[126:127], v[46:47] op_sel:[0,1,0]
	ds_read_b128 v[120:123], v118 offset:1024
	ds_read_b128 v[124:127], v118 offset:1040
	s_waitcnt lgkmcnt(2)
; #define LAS __attribute__((address_space(3)))
; template <int TY> __device__ __forceinline__ void sample_item(const Params& p, ldsp lds, int item) {
;     ...
; #pragma unroll 8
;     for (int d = dg; d < DK; d += NG) { const f32x4 s0 = __builtin_nontemporal_load((const f32x4*)(S0 + (size_t)d * DV + e4 * 4));
;         const f32x4 qa = *(const LAS f32x4*)(QK + d * 16), qb = *(const LAS f32x4*)(QK + d * 16 + 4), ka = *(const LAS f32x4*)(QK + d * 16 + 8), kb = *(const LAS f32x4*)(QK + d * 16 + 12);
;         const float dc = DECs[d];
;         o[0] += s0 * qa[0]; o[1] += s0 * qa[1]; o[2] += s0 * qa[2]; o[3] += s0 * qa[3]; o[4] += s0 * qb[0]; o[5] += s0 * qb[1]; o[6] += s0 * qb[2]; o[7] += s0 * qb[3];
;         f32x4 sn = s0 * dc; sn += v[0] * ka[0]; sn += v[1] * ka[1]; sn += v[2] * ka[2]; sn += v[3] * ka[3]; sn += v[4] * kb[0]; sn += v[5] * kb[1]; sn += v[6] * kb[2]; sn += v[7] * kb[3];
;         __builtin_nontemporal_store(sn, (f32x4*)(S1 + (size_t)d * DV + e4 * 4)); }
	v_pk_mul_f32 v[84:85], v[84:85], v[136:137] op_sel_hi:[1,0]
	v_pk_mul_f32 v[86:87], v[86:87], v[136:137] op_sel_hi:[1,0]
	v_pk_fma_f32 v[84:85], v[0:1], v[128:129], v[84:85] op_sel_hi:[1,0,1]
	v_pk_fma_f32 v[86:87], v[2:3], v[128:129], v[86:87] op_sel_hi:[1,0,1]
	v_pk_fma_f32 v[84:85], v[4:5], v[128:129], v[84:85] op_sel:[0,1,0]
	v_pk_fma_f32 v[86:87], v[6:7], v[128:129], v[86:87] op_sel:[0,1,0]
	v_pk_fma_f32 v[84:85], v[8:9], v[130:131], v[84:85] op_sel_hi:[1,0,1]
	v_pk_fma_f32 v[86:87], v[10:11], v[130:131], v[86:87] op_sel_hi:[1,0,1]
	v_pk_fma_f32 v[84:85], v[12:13], v[130:131], v[84:85] op_sel:[0,1,0]
	v_pk_fma_f32 v[86:87], v[14:15], v[130:131], v[86:87] op_sel:[0,1,0]
	v_pk_fma_f32 v[84:85], v[20:21], v[132:133], v[84:85] op_sel_hi:[1,0,1]
	v_pk_fma_f32 v[86:87], v[22:23], v[132:133], v[86:87] op_sel_hi:[1,0,1]
	v_pk_fma_f32 v[84:85], v[24:25], v[132:133], v[84:85] op_sel:[0,1,0]
	v_pk_fma_f32 v[86:87], v[26:27], v[132:133], v[86:87] op_sel:[0,1,0]
	v_pk_fma_f32 v[84:85], v[28:29], v[134:135], v[84:85] op_sel_hi:[1,0,1]
	v_pk_fma_f32 v[86:87], v[30:31], v[134:135], v[86:87] op_sel_hi:[1,0,1]
	v_pk_fma_f32 v[84:85], v[32:33], v[134:135], v[84:85] op_sel:[0,1,0]
	v_pk_fma_f32 v[86:87], v[34:35], v[134:135], v[86:87] op_sel:[0,1,0]
	global_store_dwordx4 v107, v[84:87], s[14:15] nt
	v_add_u32_e32 v107, 0x10000, v107
	global_load_dwordx4 v[84:87], v107, s[12:13] nt
	ds_read_b128 v[128:131], v118 offset:1056
	ds_read_b128 v[132:135], v118 offset:1072
	ds_read_b32 v136, v16 offset:64
	s_waitcnt vmcnt(14) lgkmcnt(3)
	v_pk_fma_f32 v[64:65], v[88:89], v[120:121], v[64:65] op_sel_hi:[1,0,1]
	v_pk_fma_f32 v[66:67], v[90:91], v[120:121], v[66:67] op_sel_hi:[1,0,1]
	v_pk_fma_f32 v[60:61], v[88:89], v[120:121], v[60:61] op_sel:[0,1,0]
	v_pk_fma_f32 v[62:63], v[90:91], v[120:121], v[62:63] op_sel:[0,1,0]
	v_pk_fma_f32 v[56:57], v[88:89], v[122:123], v[56:57] op_sel_hi:[1,0,1]
	v_pk_fma_f32 v[58:59], v[90:91], v[122:123], v[58:59] op_sel_hi:[1,0,1]
	v_pk_fma_f32 v[52:53], v[88:89], v[122:123], v[52:53] op_sel:[0,1,0]
	v_pk_fma_f32 v[54:55], v[90:91], v[122:123], v[54:55] op_sel:[0,1,0]
	v_pk_fma_f32 v[48:49], v[88:89], v[124:125], v[48:49] op_sel_hi:[1,0,1]
	v_pk_fma_f32 v[50:51], v[90:91], v[124:125], v[50:51] op_sel_hi:[1,0,1]
	v_pk_fma_f32 v[40:41], v[88:89], v[124:125], v[40:41] op_sel:[0,1,0]
	v_pk_fma_f32 v[42:43], v[90:91], v[124:125], v[42:43] op_sel:[0,1,0]
	v_pk_fma_f32 v[36:37], v[88:89], v[126:127], v[36:37] op_sel_hi:[1,0,1]
	v_pk_fma_f32 v[38:39], v[90:91], v[126:127], v[38:39] op_sel_hi:[1,0,1]
	v_pk_fma_f32 v[44:45], v[88:89], v[126:127], v[44:45] op_sel:[0,1,0]
	v_pk_fma_f32 v[46:47], v[90:91], v[126:127], v[46:47] op_sel:[0,1,0]
	ds_read_b128 v[120:123], v118 offset:1280
	ds_read_b128 v[124:127], v118 offset:1296
	s_waitcnt lgkmcnt(2)
	v_pk_mul_f32 v[88:89], v[88:89], v[136:137] op_sel_hi:[1,0]
	v_pk_mul_f32 v[90:91], v[90:91], v[136:137] op_sel_hi:[1,0]
	v_pk_fma_f32 v[88:89], v[0:1], v[128:129], v[88:89] op_sel_hi:[1,0,1]
	v_pk_fma_f32 v[90:91], v[2:3], v[128:129], v[90:91] op_sel_hi:[1,0,1]
	v_pk_fma_f32 v[88:89], v[4:5], v[128:129], v[88:89] op_sel:[0,1,0]
	v_pk_fma_f32 v[90:91], v[6:7], v[128:129], v[90:91] op_sel:[0,1,0]
	v_pk_fma_f32 v[88:89], v[8:9], v[130:131], v[88:89] op_sel_hi:[1,0,1]
	v_pk_fma_f32 v[90:91], v[10:11], v[130:131], v[90:91] op_sel_hi:[1,0,1]
	v_pk_fma_f32 v[88:89], v[12:13], v[130:131], v[88:89] op_sel:[0,1,0]
	v_pk_fma_f32 v[90:91], v[14:15], v[130:131], v[90:91] op_sel:[0,1,0]
	v_pk_fma_f32 v[88:89], v[20:21], v[132:133], v[88:89] op_sel_hi:[1,0,1]
	v_pk_fma_f32 v[90:91], v[22:23], v[132:133], v[90:91] op_sel_hi:[1,0,1]
	v_pk_fma_f32 v[88:89], v[24:25], v[132:133], v[88:89] op_sel:[0,1,0]
	v_pk_fma_f32 v[90:91], v[26:27], v[132:133], v[90:91] op_sel:[0,1,0]
	v_pk_fma_f32 v[88:89], v[28:29], v[134:135], v[88:89] op_sel_hi:[1,0,1]
	v_pk_fma_f32 v[90:91], v[30:31], v[134:135], v[90:91] op_sel_hi:[1,0,1]
	v_pk_fma_f32 v[88:89], v[32:33], v[134:135], v[88:89] op_sel:[0,1,0]
	v_pk_fma_f32 v[90:91], v[34:35], v[134:135], v[90:91] op_sel:[0,1,0]
	global_store_dwordx4 v108, v[88:91], s[14:15] nt
	v_add_u32_e32 v108, 0x10000, v108
	global_load_dwordx4 v[88:91], v108, s[12:13] nt
	ds_read_b128 v[128:131], v118 offset:1312
	ds_read_b128 v[132:135], v118 offset:1328
	ds_read_b32 v136, v16 offset:80
	s_waitcnt vmcnt(14) lgkmcnt(3)
	v_pk_fma_f32 v[64:65], v[92:93], v[120:121], v[64:65] op_sel_hi:[1,0,1]
	v_pk_fma_f32 v[66:67], v[94:95], v[120:121], v[66:67] op_sel_hi:[1,0,1]
	v_pk_fma_f32 v[60:61], v[92:93], v[120:121], v[60:61] op_sel:[0,1,0]
	v_pk_fma_f32 v[62:63], v[94:95], v[120:121], v[62:63] op_sel:[0,1,0]
	v_pk_fma_f32 v[56:57], v[92:93], v[122:123], v[56:57] op_sel_hi:[1,0,1]
	v_pk_fma_f32 v[58:59], v[94:95], v[122:123], v[58:59] op_sel_hi:[1,0,1]
	v_pk_fma_f32 v[52:53], v[92:93], v[122:123], v[52:53] op_sel:[0,1,0]
	v_pk_fma_f32 v[54:55], v[94:95], v[122:123], v[54:55] op_sel:[0,1,0]
	v_pk_fma_f32 v[48:49], v[92:93], v[124:125], v[48:49] op_sel_hi:[1,0,1]
	v_pk_fma_f32 v[50:51], v[94:95], v[124:125], v[50:51] op_sel_hi:[1,0,1]
	v_pk_fma_f32 v[40:41], v[92:93], v[124:125], v[40:41] op_sel:[0,1,0]
	v_pk_fma_f32 v[42:43], v[94:95], v[124:125], v[42:43] op_sel:[0,1,0]
	v_pk_fma_f32 v[36:37], v[92:93], v[126:127], v[36:37] op_sel_hi:[1,0,1]
	v_pk_fma_f32 v[38:39], v[94:95], v[126:127], v[38:39] op_sel_hi:[1,0,1]
	v_pk_fma_f32 v[44:45], v[92:93], v[126:127], v[44:45] op_sel:[0,1,0]
	v_pk_fma_f32 v[46:47], v[94:95], v[126:127], v[46:47] op_sel:[0,1,0]
	ds_read_b128 v[120:123], v118 offset:1536
	ds_read_b128 v[124:127], v118 offset:1552
	s_waitcnt lgkmcnt(2)
; #define LAS __attribute__((address_space(3)))
; template <int TY> __device__ __forceinline__ void sample_item(const Params& p, ldsp lds, int item) {
;     ...
; #pragma unroll 8
;     for (int d = dg; d < DK; d += NG) { const f32x4 s0 = __builtin_nontemporal_load((const f32x4*)(S0 + (size_t)d * DV + e4 * 4));
;         const f32x4 qa = *(const LAS f32x4*)(QK + d * 16), qb = *(const LAS f32x4*)(QK + d * 16 + 4), ka = *(const LAS f32x4*)(QK + d * 16 + 8), kb = *(const LAS f32x4*)(QK + d * 16 + 12);
;         const float dc = DECs[d];
;         o[0] += s0 * qa[0]; o[1] += s0 * qa[1]; o[2] += s0 * qa[2]; o[3] += s0 * qa[3]; o[4] += s0 * qb[0]; o[5] += s0 * qb[1]; o[6] += s0 * qb[2]; o[7] += s0 * qb[3];
;         f32x4 sn = s0 * dc; sn += v[0] * ka[0]; sn += v[1] * ka[1]; sn += v[2] * ka[2]; sn += v[3] * ka[3]; sn += v[4] * kb[0]; sn += v[5] * kb[1]; sn += v[6] * kb[2]; sn += v[7] * kb[3];
;         __builtin_nontemporal_store(sn, (f32x4*)(S1 + (size_t)d * DV + e4 * 4)); }
	v_pk_mul_f32 v[92:93], v[92:93], v[136:137] op_sel_hi:[1,0]
	v_pk_mul_f32 v[94:95], v[94:95], v[136:137] op_sel_hi:[1,0]
	v_pk_fma_f32 v[92:93], v[0:1], v[128:129], v[92:93] op_sel_hi:[1,0,1]
	v_pk_fma_f32 v[94:95], v[2:3], v[128:129], v[94:95] op_sel_hi:[1,0,1]
	v_pk_fma_f32 v[92:93], v[4:5], v[128:129], v[92:93] op_sel:[0,1,0]
	v_pk_fma_f32 v[94:95], v[6:7], v[128:129], v[94:95] op_sel:[0,1,0]
	v_pk_fma_f32 v[92:93], v[8:9], v[130:131], v[92:93] op_sel_hi:[1,0,1]
	v_pk_fma_f32 v[94:95], v[10:11], v[130:131], v[94:95] op_sel_hi:[1,0,1]
	v_pk_fma_f32 v[92:93], v[12:13], v[130:131], v[92:93] op_sel:[0,1,0]
	v_pk_fma_f32 v[94:95], v[14:15], v[130:131], v[94:95] op_sel:[0,1,0]
	v_pk_fma_f32 v[92:93], v[20:21], v[132:133], v[92:93] op_sel_hi:[1,0,1]
	v_pk_fma_f32 v[94:95], v[22:23], v[132:133], v[94:95] op_sel_hi:[1,0,1]
	v_pk_fma_f32 v[92:93], v[24:25], v[132:133], v[92:93] op_sel:[0,1,0]
	v_pk_fma_f32 v[94:95], v[26:27], v[132:133], v[94:95] op_sel:[0,1,0]
	v_pk_fma_f32 v[92:93], v[28:29], v[134:135], v[92:93] op_sel_hi:[1,0,1]
	v_pk_fma_f32 v[94:95], v[30:31], v[134:135], v[94:95] op_sel_hi:[1,0,1]
	v_pk_fma_f32 v[92:93], v[32:33], v[134:135], v[92:93] op_sel:[0,1,0]
	v_pk_fma_f32 v[94:95], v[34:35], v[134:135], v[94:95] op_sel:[0,1,0]
	global_store_dwordx4 v109, v[92:95], s[14:15] nt
	v_add_u32_e32 v109, 0x10000, v109
	global_load_dwordx4 v[92:95], v109, s[12:13] nt
	ds_read_b128 v[128:131], v118 offset:1568
	ds_read_b128 v[132:135], v118 offset:1584
	ds_read_b32 v136, v16 offset:96
	s_waitcnt vmcnt(14) lgkmcnt(3)
	v_pk_fma_f32 v[64:65], v[96:97], v[120:121], v[64:65] op_sel_hi:[1,0,1]
	v_pk_fma_f32 v[66:67], v[98:99], v[120:121], v[66:67] op_sel_hi:[1,0,1]
	v_pk_fma_f32 v[60:61], v[96:97], v[120:121], v[60:61] op_sel:[0,1,0]
	v_pk_fma_f32 v[62:63], v[98:99], v[120:121], v[62:63] op_sel:[0,1,0]
	v_pk_fma_f32 v[56:57], v[96:97], v[122:123], v[56:57] op_sel_hi:[1,0,1]
	v_pk_fma_f32 v[58:59], v[98:99], v[122:123], v[58:59] op_sel_hi:[1,0,1]
	v_pk_fma_f32 v[52:53], v[96:97], v[122:123], v[52:53] op_sel:[0,1,0]
	v_pk_fma_f32 v[54:55], v[98:99], v[122:123], v[54:55] op_sel:[0,1,0]
	v_pk_fma_f32 v[48:49], v[96:97], v[124:125], v[48:49] op_sel_hi:[1,0,1]
	v_pk_fma_f32 v[50:51], v[98:99], v[124:125], v[50:51] op_sel_hi:[1,0,1]
	v_pk_fma_f32 v[40:41], v[96:97], v[124:125], v[40:41] op_sel:[0,1,0]
	v_pk_fma_f32 v[42:43], v[98:99], v[124:125], v[42:43] op_sel:[0,1,0]
	v_pk_fma_f32 v[36:37], v[96:97], v[126:127], v[36:37] op_sel_hi:[1,0,1]
	v_pk_fma_f32 v[38:39], v[98:99], v[126:127], v[38:39] op_sel_hi:[1,0,1]
	v_pk_fma_f32 v[44:45], v[96:97], v[126:127], v[44:45] op_sel:[0,1,0]
	v_pk_fma_f32 v[46:47], v[98:99], v[126:127], v[46:47] op_sel:[0,1,0]
	ds_read_b128 v[120:123], v118 offset:1792
	ds_read_b128 v[124:127], v118 offset:1808
	s_waitcnt lgkmcnt(2)
	v_pk_mul_f32 v[96:97], v[96:97], v[136:137] op_sel_hi:[1,0]
	v_pk_mul_f32 v[98:99], v[98:99], v[136:137] op_sel_hi:[1,0]
	v_pk_fma_f32 v[96:97], v[0:1], v[128:129], v[96:97] op_sel_hi:[1,0,1]
	v_pk_fma_f32 v[98:99], v[2:3], v[128:129], v[98:99] op_sel_hi:[1,0,1]
	v_pk_fma_f32 v[96:97], v[4:5], v[128:129], v[96:97] op_sel:[0,1,0]
	v_pk_fma_f32 v[98:99], v[6:7], v[128:129], v[98:99] op_sel:[0,1,0]
	v_pk_fma_f32 v[96:97], v[8:9], v[130:131], v[96:97] op_sel_hi:[1,0,1]
	v_pk_fma_f32 v[98:99], v[10:11], v[130:131], v[98:99] op_sel_hi:[1,0,1]
	v_pk_fma_f32 v[96:97], v[12:13], v[130:131], v[96:97] op_sel:[0,1,0]
	v_pk_fma_f32 v[98:99], v[14:15], v[130:131], v[98:99] op_sel:[0,1,0]
	v_pk_fma_f32 v[96:97], v[20:21], v[132:133], v[96:97] op_sel_hi:[1,0,1]
	v_pk_fma_f32 v[98:99], v[22:23], v[132:133], v[98:99] op_sel_hi:[1,0,1]
	v_pk_fma_f32 v[96:97], v[24:25], v[132:133], v[96:97] op_sel:[0,1,0]
	v_pk_fma_f32 v[98:99], v[26:27], v[132:133], v[98:99] op_sel:[0,1,0]
	v_pk_fma_f32 v[96:97], v[28:29], v[134:135], v[96:97] op_sel_hi:[1,0,1]
	v_pk_fma_f32 v[98:99], v[30:31], v[134:135], v[98:99] op_sel_hi:[1,0,1]
	v_pk_fma_f32 v[96:97], v[32:33], v[134:135], v[96:97] op_sel:[0,1,0]
	v_pk_fma_f32 v[98:99], v[34:35], v[134:135], v[98:99] op_sel:[0,1,0]
	global_store_dwordx4 v110, v[96:99], s[14:15] nt
	v_add_u32_e32 v110, 0x10000, v110
	global_load_dwordx4 v[96:99], v110, s[12:13] nt
	ds_read_b128 v[128:131], v118 offset:1824
	ds_read_b128 v[132:135], v118 offset:1840
	ds_read_b32 v136, v16 offset:112
	s_waitcnt vmcnt(14) lgkmcnt(3)
	v_pk_fma_f32 v[64:65], v[100:101], v[120:121], v[64:65] op_sel_hi:[1,0,1]
	v_pk_fma_f32 v[66:67], v[102:103], v[120:121], v[66:67] op_sel_hi:[1,0,1]
	v_pk_fma_f32 v[60:61], v[100:101], v[120:121], v[60:61] op_sel:[0,1,0]
	v_pk_fma_f32 v[62:63], v[102:103], v[120:121], v[62:63] op_sel:[0,1,0]
	v_pk_fma_f32 v[56:57], v[100:101], v[122:123], v[56:57] op_sel_hi:[1,0,1]
	v_pk_fma_f32 v[58:59], v[102:103], v[122:123], v[58:59] op_sel_hi:[1,0,1]
	v_pk_fma_f32 v[52:53], v[100:101], v[122:123], v[52:53] op_sel:[0,1,0]
	v_pk_fma_f32 v[54:55], v[102:103], v[122:123], v[54:55] op_sel:[0,1,0]
	v_pk_fma_f32 v[48:49], v[100:101], v[124:125], v[48:49] op_sel_hi:[1,0,1]
	v_pk_fma_f32 v[50:51], v[102:103], v[124:125], v[50:51] op_sel_hi:[1,0,1]
	v_pk_fma_f32 v[40:41], v[100:101], v[124:125], v[40:41] op_sel:[0,1,0]
	v_pk_fma_f32 v[42:43], v[102:103], v[124:125], v[42:43] op_sel:[0,1,0]
	v_pk_fma_f32 v[36:37], v[100:101], v[126:127], v[36:37] op_sel_hi:[1,0,1]
	v_pk_fma_f32 v[38:39], v[102:103], v[126:127], v[38:39] op_sel_hi:[1,0,1]
	v_pk_fma_f32 v[44:45], v[100:101], v[126:127], v[44:45] op_sel:[0,1,0]
	v_pk_fma_f32 v[46:47], v[102:103], v[126:127], v[46:47] op_sel:[0,1,0]
	ds_read_b128 v[120:123], v118 offset:2048
	ds_read_b128 v[124:127], v118 offset:2064
	s_waitcnt lgkmcnt(2)
; #define LAS __attribute__((address_space(3)))
; template <int TY> __device__ __forceinline__ void sample_item(const Params& p, ldsp lds, int item) {
;     ...
; #pragma unroll 8
;     for (int d = dg; d < DK; d += NG) { const f32x4 s0 = __builtin_nontemporal_load((const f32x4*)(S0 + (size_t)d * DV + e4 * 4));
;         const f32x4 qa = *(const LAS f32x4*)(QK + d * 16), qb = *(const LAS f32x4*)(QK + d * 16 + 4), ka = *(const LAS f32x4*)(QK + d * 16 + 8), kb = *(const LAS f32x4*)(QK + d * 16 + 12);
;         const float dc = DECs[d];
;         o[0] += s0 * qa[0]; o[1] += s0 * qa[1]; o[2] += s0 * qa[2]; o[3] += s0 * qa[3]; o[4] += s0 * qb[0]; o[5] += s0 * qb[1]; o[6] += s0 * qb[2]; o[7] += s0 * qb[3];
;         f32x4 sn = s0 * dc; sn += v[0] * ka[0]; sn += v[1] * ka[1]; sn += v[2] * ka[2]; sn += v[3] * ka[3]; sn += v[4] * kb[0]; sn += v[5] * kb[1]; sn += v[6] * kb[2]; sn += v[7] * kb[3];
;         __builtin_nontemporal_store(sn, (f32x4*)(S1 + (size_t)d * DV + e4 * 4)); }
	v_pk_mul_f32 v[100:101], v[100:101], v[136:137] op_sel_hi:[1,0]
	v_pk_mul_f32 v[102:103], v[102:103], v[136:137] op_sel_hi:[1,0]
	v_pk_fma_f32 v[100:101], v[0:1], v[128:129], v[100:101] op_sel_hi:[1,0,1]
	v_pk_fma_f32 v[102:103], v[2:3], v[128:129], v[102:103] op_sel_hi:[1,0,1]
	v_pk_fma_f32 v[100:101], v[4:5], v[128:129], v[100:101] op_sel:[0,1,0]
	v_pk_fma_f32 v[102:103], v[6:7], v[128:129], v[102:103] op_sel:[0,1,0]
	v_pk_fma_f32 v[100:101], v[8:9], v[130:131], v[100:101] op_sel_hi:[1,0,1]
	v_pk_fma_f32 v[102:103], v[10:11], v[130:131], v[102:103] op_sel_hi:[1,0,1]
	v_pk_fma_f32 v[100:101], v[12:13], v[130:131], v[100:101] op_sel:[0,1,0]
	v_pk_fma_f32 v[102:103], v[14:15], v[130:131], v[102:103] op_sel:[0,1,0]
	v_pk_fma_f32 v[100:101], v[20:21], v[132:133], v[100:101] op_sel_hi:[1,0,1]
	v_pk_fma_f32 v[102:103], v[22:23], v[132:133], v[102:103] op_sel_hi:[1,0,1]
	v_pk_fma_f32 v[100:101], v[24:25], v[132:133], v[100:101] op_sel:[0,1,0]
	v_pk_fma_f32 v[102:103], v[26:27], v[132:133], v[102:103] op_sel:[0,1,0]
	v_pk_fma_f32 v[100:101], v[28:29], v[134:135], v[100:101] op_sel_hi:[1,0,1]
	v_pk_fma_f32 v[102:103], v[30:31], v[134:135], v[102:103] op_sel_hi:[1,0,1]
	v_pk_fma_f32 v[100:101], v[32:33], v[134:135], v[100:101] op_sel:[0,1,0]
	v_pk_fma_f32 v[102:103], v[34:35], v[134:135], v[102:103] op_sel:[0,1,0]
	global_store_dwordx4 v111, v[100:103], s[14:15] nt
	v_add_u32_e32 v111, 0x10000, v111
	global_load_dwordx4 v[100:103], v111, s[12:13] nt
	v_add_u32_e32 v118, 0x800, v118
	v_add_u32_e32 v16, 0x80, v16
	s_add_i32 s16, s16, 1
	s_cmp_lt_u32 s16, 6
	s_cbranch_scc1 .Lsm2_stream_loop
	ds_read_b128 v[128:131], v118 offset:32
	ds_read_b128 v[132:135], v118 offset:48
	ds_read_b32 v136, v16 offset:0
	s_waitcnt vmcnt(14) lgkmcnt(3)
	v_pk_fma_f32 v[64:65], v[72:73], v[120:121], v[64:65] op_sel_hi:[1,0,1]
	v_pk_fma_f32 v[66:67], v[74:75], v[120:121], v[66:67] op_sel_hi:[1,0,1]
	v_pk_fma_f32 v[60:61], v[72:73], v[120:121], v[60:61] op_sel:[0,1,0]
	v_pk_fma_f32 v[62:63], v[74:75], v[120:121], v[62:63] op_sel:[0,1,0]
	v_pk_fma_f32 v[56:57], v[72:73], v[122:123], v[56:57] op_sel_hi:[1,0,1]
	v_pk_fma_f32 v[58:59], v[74:75], v[122:123], v[58:59] op_sel_hi:[1,0,1]
	v_pk_fma_f32 v[52:53], v[72:73], v[122:123], v[52:53] op_sel:[0,1,0]
	v_pk_fma_f32 v[54:55], v[74:75], v[122:123], v[54:55] op_sel:[0,1,0]
	v_pk_fma_f32 v[48:49], v[72:73], v[124:125], v[48:49] op_sel_hi:[1,0,1]
	v_pk_fma_f32 v[50:51], v[74:75], v[124:125], v[50:51] op_sel_hi:[1,0,1]
	v_pk_fma_f32 v[40:41], v[72:73], v[124:125], v[40:41] op_sel:[0,1,0]
	v_pk_fma_f32 v[42:43], v[74:75], v[124:125], v[42:43] op_sel:[0,1,0]
	v_pk_fma_f32 v[36:37], v[72:73], v[126:127], v[36:37] op_sel_hi:[1,0,1]
	v_pk_fma_f32 v[38:39], v[74:75], v[126:127], v[38:39] op_sel_hi:[1,0,1]
	v_pk_fma_f32 v[44:45], v[72:73], v[126:127], v[44:45] op_sel:[0,1,0]
	v_pk_fma_f32 v[46:47], v[74:75], v[126:127], v[46:47] op_sel:[0,1,0]
	ds_read_b128 v[120:123], v118 offset:256
	ds_read_b128 v[124:127], v118 offset:272
	s_waitcnt lgkmcnt(2)
	v_pk_mul_f32 v[72:73], v[72:73], v[136:137] op_sel_hi:[1,0]
	v_pk_mul_f32 v[74:75], v[74:75], v[136:137] op_sel_hi:[1,0]
	v_pk_fma_f32 v[72:73], v[0:1], v[128:129], v[72:73] op_sel_hi:[1,0,1]
	v_pk_fma_f32 v[74:75], v[2:3], v[128:129], v[74:75] op_sel_hi:[1,0,1]
	v_pk_fma_f32 v[72:73], v[4:5], v[128:129], v[72:73] op_sel:[0,1,0]
	v_pk_fma_f32 v[74:75], v[6:7], v[128:129], v[74:75] op_sel:[0,1,0]
	v_pk_fma_f32 v[72:73], v[8:9], v[130:131], v[72:73] op_sel_hi:[1,0,1]
	v_pk_fma_f32 v[74:75], v[10:11], v[130:131], v[74:75] op_sel_hi:[1,0,1]
	v_pk_fma_f32 v[72:73], v[12:13], v[130:131], v[72:73] op_sel:[0,1,0]
	v_pk_fma_f32 v[74:75], v[14:15], v[130:131], v[74:75] op_sel:[0,1,0]
	v_pk_fma_f32 v[72:73], v[20:21], v[132:133], v[72:73] op_sel_hi:[1,0,1]
	v_pk_fma_f32 v[74:75], v[22:23], v[132:133], v[74:75] op_sel_hi:[1,0,1]
	v_pk_fma_f32 v[72:73], v[24:25], v[132:133], v[72:73] op_sel:[0,1,0]
	v_pk_fma_f32 v[74:75], v[26:27], v[132:133], v[74:75] op_sel:[0,1,0]
	v_pk_fma_f32 v[72:73], v[28:29], v[134:135], v[72:73] op_sel_hi:[1,0,1]
	v_pk_fma_f32 v[74:75], v[30:31], v[134:135], v[74:75] op_sel_hi:[1,0,1]
	v_pk_fma_f32 v[72:73], v[32:33], v[134:135], v[72:73] op_sel:[0,1,0]
	v_pk_fma_f32 v[74:75], v[34:35], v[134:135], v[74:75] op_sel:[0,1,0]
	global_store_dwordx4 v104, v[72:75], s[14:15] nt
	ds_read_b128 v[128:131], v118 offset:288
	ds_read_b128 v[132:135], v118 offset:304
	ds_read_b32 v136, v16 offset:16
	s_waitcnt vmcnt(13) lgkmcnt(3)
	v_pk_fma_f32 v[64:65], v[76:77], v[120:121], v[64:65] op_sel_hi:[1,0,1]
	v_pk_fma_f32 v[66:67], v[78:79], v[120:121], v[66:67] op_sel_hi:[1,0,1]
	v_pk_fma_f32 v[60:61], v[76:77], v[120:121], v[60:61] op_sel:[0,1,0]
	v_pk_fma_f32 v[62:63], v[78:79], v[120:121], v[62:63] op_sel:[0,1,0]
	v_pk_fma_f32 v[56:57], v[76:77], v[122:123], v[56:57] op_sel_hi:[1,0,1]
	v_pk_fma_f32 v[58:59], v[78:79], v[122:123], v[58:59] op_sel_hi:[1,0,1]
	v_pk_fma_f32 v[52:53], v[76:77], v[122:123], v[52:53] op_sel:[0,1,0]
	v_pk_fma_f32 v[54:55], v[78:79], v[122:123], v[54:55] op_sel:[0,1,0]
	v_pk_fma_f32 v[48:49], v[76:77], v[124:125], v[48:49] op_sel_hi:[1,0,1]
	v_pk_fma_f32 v[50:51], v[78:79], v[124:125], v[50:51] op_sel_hi:[1,0,1]
	v_pk_fma_f32 v[40:41], v[76:77], v[124:125], v[40:41] op_sel:[0,1,0]
	v_pk_fma_f32 v[42:43], v[78:79], v[124:125], v[42:43] op_sel:[0,1,0]
	v_pk_fma_f32 v[36:37], v[76:77], v[126:127], v[36:37] op_sel_hi:[1,0,1]
	v_pk_fma_f32 v[38:39], v[78:79], v[126:127], v[38:39] op_sel_hi:[1,0,1]
	v_pk_fma_f32 v[44:45], v[76:77], v[126:127], v[44:45] op_sel:[0,1,0]
	v_pk_fma_f32 v[46:47], v[78:79], v[126:127], v[46:47] op_sel:[0,1,0]
	ds_read_b128 v[120:123], v118 offset:512
	ds_read_b128 v[124:127], v118 offset:528
	s_waitcnt lgkmcnt(2)
; #define LAS __attribute__((address_space(3)))
; template <int TY> __device__ __forceinline__ void sample_item(const Params& p, ldsp lds, int item) {
;     ...
; #pragma unroll 8
;     for (int d = dg; d < DK; d += NG) { const f32x4 s0 = __builtin_nontemporal_load((const f32x4*)(S0 + (size_t)d * DV + e4 * 4));
;         const f32x4 qa = *(const LAS f32x4*)(QK + d * 16), qb = *(const LAS f32x4*)(QK + d * 16 + 4), ka = *(const LAS f32x4*)(QK + d * 16 + 8), kb = *(const LAS f32x4*)(QK + d * 16 + 12);
;         const float dc = DECs[d];
;         o[0] += s0 * qa[0]; o[1] += s0 * qa[1]; o[2] += s0 * qa[2]; o[3] += s0 * qa[3]; o[4] += s0 * qb[0]; o[5] += s0 * qb[1]; o[6] += s0 * qb[2]; o[7] += s0 * qb[3];
;         f32x4 sn = s0 * dc; sn += v[0] * ka[0]; sn += v[1] * ka[1]; sn += v[2] * ka[2]; sn += v[3] * ka[3]; sn += v[4] * kb[0]; sn += v[5] * kb[1]; sn += v[6] * kb[2]; sn += v[7] * kb[3];
;         __builtin_nontemporal_store(sn, (f32x4*)(S1 + (size_t)d * DV + e4 * 4)); }
	v_pk_mul_f32 v[76:77], v[76:77], v[136:137] op_sel_hi:[1,0]
	v_pk_mul_f32 v[78:79], v[78:79], v[136:137] op_sel_hi:[1,0]
	v_pk_fma_f32 v[76:77], v[0:1], v[128:129], v[76:77] op_sel_hi:[1,0,1]
	v_pk_fma_f32 v[78:79], v[2:3], v[128:129], v[78:79] op_sel_hi:[1,0,1]
	v_pk_fma_f32 v[76:77], v[4:5], v[128:129], v[76:77] op_sel:[0,1,0]
	v_pk_fma_f32 v[78:79], v[6:7], v[128:129], v[78:79] op_sel:[0,1,0]
	v_pk_fma_f32 v[76:77], v[8:9], v[130:131], v[76:77] op_sel_hi:[1,0,1]
	v_pk_fma_f32 v[78:79], v[10:11], v[130:131], v[78:79] op_sel_hi:[1,0,1]
	v_pk_fma_f32 v[76:77], v[12:13], v[130:131], v[76:77] op_sel:[0,1,0]
	v_pk_fma_f32 v[78:79], v[14:15], v[130:131], v[78:79] op_sel:[0,1,0]
	v_pk_fma_f32 v[76:77], v[20:21], v[132:133], v[76:77] op_sel_hi:[1,0,1]
	v_pk_fma_f32 v[78:79], v[22:23], v[132:133], v[78:79] op_sel_hi:[1,0,1]
	v_pk_fma_f32 v[76:77], v[24:25], v[132:133], v[76:77] op_sel:[0,1,0]
	v_pk_fma_f32 v[78:79], v[26:27], v[132:133], v[78:79] op_sel:[0,1,0]
	v_pk_fma_f32 v[76:77], v[28:29], v[134:135], v[76:77] op_sel_hi:[1,0,1]
	v_pk_fma_f32 v[78:79], v[30:31], v[134:135], v[78:79] op_sel_hi:[1,0,1]
	v_pk_fma_f32 v[76:77], v[32:33], v[134:135], v[76:77] op_sel:[0,1,0]
	v_pk_fma_f32 v[78:79], v[34:35], v[134:135], v[78:79] op_sel:[0,1,0]
	global_store_dwordx4 v105, v[76:79], s[14:15] nt
	ds_read_b128 v[128:131], v118 offset:544
	ds_read_b128 v[132:135], v118 offset:560
	ds_read_b32 v136, v16 offset:32
	s_waitcnt vmcnt(12) lgkmcnt(3)
	v_pk_fma_f32 v[64:65], v[80:81], v[120:121], v[64:65] op_sel_hi:[1,0,1]
	v_pk_fma_f32 v[66:67], v[82:83], v[120:121], v[66:67] op_sel_hi:[1,0,1]
	v_pk_fma_f32 v[60:61], v[80:81], v[120:121], v[60:61] op_sel:[0,1,0]
	v_pk_fma_f32 v[62:63], v[82:83], v[120:121], v[62:63] op_sel:[0,1,0]
	v_pk_fma_f32 v[56:57], v[80:81], v[122:123], v[56:57] op_sel_hi:[1,0,1]
	v_pk_fma_f32 v[58:59], v[82:83], v[122:123], v[58:59] op_sel_hi:[1,0,1]
	v_pk_fma_f32 v[52:53], v[80:81], v[122:123], v[52:53] op_sel:[0,1,0]
	v_pk_fma_f32 v[54:55], v[82:83], v[122:123], v[54:55] op_sel:[0,1,0]
	v_pk_fma_f32 v[48:49], v[80:81], v[124:125], v[48:49] op_sel_hi:[1,0,1]
	v_pk_fma_f32 v[50:51], v[82:83], v[124:125], v[50:51] op_sel_hi:[1,0,1]
	v_pk_fma_f32 v[40:41], v[80:81], v[124:125], v[40:41] op_sel:[0,1,0]
	v_pk_fma_f32 v[42:43], v[82:83], v[124:125], v[42:43] op_sel:[0,1,0]
	v_pk_fma_f32 v[36:37], v[80:81], v[126:127], v[36:37] op_sel_hi:[1,0,1]
	v_pk_fma_f32 v[38:39], v[82:83], v[126:127], v[38:39] op_sel_hi:[1,0,1]
	v_pk_fma_f32 v[44:45], v[80:81], v[126:127], v[44:45] op_sel:[0,1,0]
	v_pk_fma_f32 v[46:47], v[82:83], v[126:127], v[46:47] op_sel:[0,1,0]
	ds_read_b128 v[120:123], v118 offset:768
	ds_read_b128 v[124:127], v118 offset:784
	s_waitcnt lgkmcnt(2)
	v_pk_mul_f32 v[80:81], v[80:81], v[136:137] op_sel_hi:[1,0]
	v_pk_mul_f32 v[82:83], v[82:83], v[136:137] op_sel_hi:[1,0]
	v_pk_fma_f32 v[80:81], v[0:1], v[128:129], v[80:81] op_sel_hi:[1,0,1]
	v_pk_fma_f32 v[82:83], v[2:3], v[128:129], v[82:83] op_sel_hi:[1,0,1]
	v_pk_fma_f32 v[80:81], v[4:5], v[128:129], v[80:81] op_sel:[0,1,0]
	v_pk_fma_f32 v[82:83], v[6:7], v[128:129], v[82:83] op_sel:[0,1,0]
	v_pk_fma_f32 v[80:81], v[8:9], v[130:131], v[80:81] op_sel_hi:[1,0,1]
	v_pk_fma_f32 v[82:83], v[10:11], v[130:131], v[82:83] op_sel_hi:[1,0,1]
	v_pk_fma_f32 v[80:81], v[12:13], v[130:131], v[80:81] op_sel:[0,1,0]
	v_pk_fma_f32 v[82:83], v[14:15], v[130:131], v[82:83] op_sel:[0,1,0]
	v_pk_fma_f32 v[80:81], v[20:21], v[132:133], v[80:81] op_sel_hi:[1,0,1]
	v_pk_fma_f32 v[82:83], v[22:23], v[132:133], v[82:83] op_sel_hi:[1,0,1]
	v_pk_fma_f32 v[80:81], v[24:25], v[132:133], v[80:81] op_sel:[0,1,0]
	v_pk_fma_f32 v[82:83], v[26:27], v[132:133], v[82:83] op_sel:[0,1,0]
	v_pk_fma_f32 v[80:81], v[28:29], v[134:135], v[80:81] op_sel_hi:[1,0,1]
	v_pk_fma_f32 v[82:83], v[30:31], v[134:135], v[82:83] op_sel_hi:[1,0,1]
	v_pk_fma_f32 v[80:81], v[32:33], v[134:135], v[80:81] op_sel:[0,1,0]
	v_pk_fma_f32 v[82:83], v[34:35], v[134:135], v[82:83] op_sel:[0,1,0]
	global_store_dwordx4 v106, v[80:83], s[14:15] nt
	ds_read_b128 v[128:131], v118 offset:800
	ds_read_b128 v[132:135], v118 offset:816
	ds_read_b32 v136, v16 offset:48
	s_waitcnt vmcnt(11) lgkmcnt(3)
	v_pk_fma_f32 v[64:65], v[84:85], v[120:121], v[64:65] op_sel_hi:[1,0,1]
	v_pk_fma_f32 v[66:67], v[86:87], v[120:121], v[66:67] op_sel_hi:[1,0,1]
	v_pk_fma_f32 v[60:61], v[84:85], v[120:121], v[60:61] op_sel:[0,1,0]
	v_pk_fma_f32 v[62:63], v[86:87], v[120:121], v[62:63] op_sel:[0,1,0]
	v_pk_fma_f32 v[56:57], v[84:85], v[122:123], v[56:57] op_sel_hi:[1,0,1]
	v_pk_fma_f32 v[58:59], v[86:87], v[122:123], v[58:59] op_sel_hi:[1,0,1]
	v_pk_fma_f32 v[52:53], v[84:85], v[122:123], v[52:53] op_sel:[0,1,0]
	v_pk_fma_f32 v[54:55], v[86:87], v[122:123], v[54:55] op_sel:[0,1,0]
	v_pk_fma_f32 v[48:49], v[84:85], v[124:125], v[48:49] op_sel_hi:[1,0,1]
	v_pk_fma_f32 v[50:51], v[86:87], v[124:125], v[50:51] op_sel_hi:[1,0,1]
	v_pk_fma_f32 v[40:41], v[84:85], v[124:125], v[40:41] op_sel:[0,1,0]
	v_pk_fma_f32 v[42:43], v[86:87], v[124:125], v[42:43] op_sel:[0,1,0]
	v_pk_fma_f32 v[36:37], v[84:85], v[126:127], v[36:37] op_sel_hi:[1,0,1]
	v_pk_fma_f32 v[38:39], v[86:87], v[126:127], v[38:39] op_sel_hi:[1,0,1]
	v_pk_fma_f32 v[44:45], v[84:85], v[126:127], v[44:45] op_sel:[0,1,0]
	v_pk_fma_f32 v[46:47], v[86:87], v[126:127], v[46:47] op_sel:[0,1,0]
	ds_read_b128 v[120:123], v118 offset:1024
	ds_read_b128 v[124:127], v118 offset:1040
	s_waitcnt lgkmcnt(2)
; #define LAS __attribute__((address_space(3)))
; template <int TY> __device__ __forceinline__ void sample_item(const Params& p, ldsp lds, int item) {
;     ...
; #pragma unroll 8
;     for (int d = dg; d < DK; d += NG) { const f32x4 s0 = __builtin_nontemporal_load((const f32x4*)(S0 + (size_t)d * DV + e4 * 4));
;         const f32x4 qa = *(const LAS f32x4*)(QK + d * 16), qb = *(const LAS f32x4*)(QK + d * 16 + 4), ka = *(const LAS f32x4*)(QK + d * 16 + 8), kb = *(const LAS f32x4*)(QK + d * 16 + 12);
;         const float dc = DECs[d];
;         o[0] += s0 * qa[0]; o[1] += s0 * qa[1]; o[2] += s0 * qa[2]; o[3] += s0 * qa[3]; o[4] += s0 * qb[0]; o[5] += s0 * qb[1]; o[6] += s0 * qb[2]; o[7] += s0 * qb[3];
;         f32x4 sn = s0 * dc; sn += v[0] * ka[0]; sn += v[1] * ka[1]; sn += v[2] * ka[2]; sn += v[3] * ka[3]; sn += v[4] * kb[0]; sn += v[5] * kb[1]; sn += v[6] * kb[2]; sn += v[7] * kb[3];
;         __builtin_nontemporal_store(sn, (f32x4*)(S1 + (size_t)d * DV + e4 * 4)); }
	v_pk_mul_f32 v[84:85], v[84:85], v[136:137] op_sel_hi:[1,0]
	v_pk_mul_f32 v[86:87], v[86:87], v[136:137] op_sel_hi:[1,0]
	v_pk_fma_f32 v[84:85], v[0:1], v[128:129], v[84:85] op_sel_hi:[1,0,1]
	v_pk_fma_f32 v[86:87], v[2:3], v[128:129], v[86:87] op_sel_hi:[1,0,1]
	v_pk_fma_f32 v[84:85], v[4:5], v[128:129], v[84:85] op_sel:[0,1,0]
	v_pk_fma_f32 v[86:87], v[6:7], v[128:129], v[86:87] op_sel:[0,1,0]
	v_pk_fma_f32 v[84:85], v[8:9], v[130:131], v[84:85] op_sel_hi:[1,0,1]
	v_pk_fma_f32 v[86:87], v[10:11], v[130:131], v[86:87] op_sel_hi:[1,0,1]
	v_pk_fma_f32 v[84:85], v[12:13], v[130:131], v[84:85] op_sel:[0,1,0]
	v_pk_fma_f32 v[86:87], v[14:15], v[130:131], v[86:87] op_sel:[0,1,0]
	v_pk_fma_f32 v[84:85], v[20:21], v[132:133], v[84:85] op_sel_hi:[1,0,1]
	v_pk_fma_f32 v[86:87], v[22:23], v[132:133], v[86:87] op_sel_hi:[1,0,1]
	v_pk_fma_f32 v[84:85], v[24:25], v[132:133], v[84:85] op_sel:[0,1,0]
	v_pk_fma_f32 v[86:87], v[26:27], v[132:133], v[86:87] op_sel:[0,1,0]
	v_pk_fma_f32 v[84:85], v[28:29], v[134:135], v[84:85] op_sel_hi:[1,0,1]
	v_pk_fma_f32 v[86:87], v[30:31], v[134:135], v[86:87] op_sel_hi:[1,0,1]
	v_pk_fma_f32 v[84:85], v[32:33], v[134:135], v[84:85] op_sel:[0,1,0]
	v_pk_fma_f32 v[86:87], v[34:35], v[134:135], v[86:87] op_sel:[0,1,0]
	global_store_dwordx4 v107, v[84:87], s[14:15] nt
	ds_read_b128 v[128:131], v118 offset:1056
	ds_read_b128 v[132:135], v118 offset:1072
	ds_read_b32 v136, v16 offset:64
	s_waitcnt vmcnt(10) lgkmcnt(3)
	v_pk_fma_f32 v[64:65], v[88:89], v[120:121], v[64:65] op_sel_hi:[1,0,1]
	v_pk_fma_f32 v[66:67], v[90:91], v[120:121], v[66:67] op_sel_hi:[1,0,1]
	v_pk_fma_f32 v[60:61], v[88:89], v[120:121], v[60:61] op_sel:[0,1,0]
	v_pk_fma_f32 v[62:63], v[90:91], v[120:121], v[62:63] op_sel:[0,1,0]
	v_pk_fma_f32 v[56:57], v[88:89], v[122:123], v[56:57] op_sel_hi:[1,0,1]
	v_pk_fma_f32 v[58:59], v[90:91], v[122:123], v[58:59] op_sel_hi:[1,0,1]
	v_pk_fma_f32 v[52:53], v[88:89], v[122:123], v[52:53] op_sel:[0,1,0]
	v_pk_fma_f32 v[54:55], v[90:91], v[122:123], v[54:55] op_sel:[0,1,0]
	v_pk_fma_f32 v[48:49], v[88:89], v[124:125], v[48:49] op_sel_hi:[1,0,1]
	v_pk_fma_f32 v[50:51], v[90:91], v[124:125], v[50:51] op_sel_hi:[1,0,1]
	v_pk_fma_f32 v[40:41], v[88:89], v[124:125], v[40:41] op_sel:[0,1,0]
	v_pk_fma_f32 v[42:43], v[90:91], v[124:125], v[42:43] op_sel:[0,1,0]
	v_pk_fma_f32 v[36:37], v[88:89], v[126:127], v[36:37] op_sel_hi:[1,0,1]
	v_pk_fma_f32 v[38:39], v[90:91], v[126:127], v[38:39] op_sel_hi:[1,0,1]
	v_pk_fma_f32 v[44:45], v[88:89], v[126:127], v[44:45] op_sel:[0,1,0]
	v_pk_fma_f32 v[46:47], v[90:91], v[126:127], v[46:47] op_sel:[0,1,0]
	ds_read_b128 v[120:123], v118 offset:1280
	ds_read_b128 v[124:127], v118 offset:1296
	s_waitcnt lgkmcnt(2)
	v_pk_mul_f32 v[88:89], v[88:89], v[136:137] op_sel_hi:[1,0]
	v_pk_mul_f32 v[90:91], v[90:91], v[136:137] op_sel_hi:[1,0]
	v_pk_fma_f32 v[88:89], v[0:1], v[128:129], v[88:89] op_sel_hi:[1,0,1]
	v_pk_fma_f32 v[90:91], v[2:3], v[128:129], v[90:91] op_sel_hi:[1,0,1]
	v_pk_fma_f32 v[88:89], v[4:5], v[128:129], v[88:89] op_sel:[0,1,0]
	v_pk_fma_f32 v[90:91], v[6:7], v[128:129], v[90:91] op_sel:[0,1,0]
	v_pk_fma_f32 v[88:89], v[8:9], v[130:131], v[88:89] op_sel_hi:[1,0,1]
	v_pk_fma_f32 v[90:91], v[10:11], v[130:131], v[90:91] op_sel_hi:[1,0,1]
	v_pk_fma_f32 v[88:89], v[12:13], v[130:131], v[88:89] op_sel:[0,1,0]
	v_pk_fma_f32 v[90:91], v[14:15], v[130:131], v[90:91] op_sel:[0,1,0]
	v_pk_fma_f32 v[88:89], v[20:21], v[132:133], v[88:89] op_sel_hi:[1,0,1]
	v_pk_fma_f32 v[90:91], v[22:23], v[132:133], v[90:91] op_sel_hi:[1,0,1]
	v_pk_fma_f32 v[88:89], v[24:25], v[132:133], v[88:89] op_sel:[0,1,0]
	v_pk_fma_f32 v[90:91], v[26:27], v[132:133], v[90:91] op_sel:[0,1,0]
	v_pk_fma_f32 v[88:89], v[28:29], v[134:135], v[88:89] op_sel_hi:[1,0,1]
	v_pk_fma_f32 v[90:91], v[30:31], v[134:135], v[90:91] op_sel_hi:[1,0,1]
	v_pk_fma_f32 v[88:89], v[32:33], v[134:135], v[88:89] op_sel:[0,1,0]
	v_pk_fma_f32 v[90:91], v[34:35], v[134:135], v[90:91] op_sel:[0,1,0]
	global_store_dwordx4 v108, v[88:91], s[14:15] nt
	ds_read_b128 v[128:131], v118 offset:1312
	ds_read_b128 v[132:135], v118 offset:1328
	ds_read_b32 v136, v16 offset:80
	s_waitcnt vmcnt(9) lgkmcnt(3)
	v_pk_fma_f32 v[64:65], v[92:93], v[120:121], v[64:65] op_sel_hi:[1,0,1]
	v_pk_fma_f32 v[66:67], v[94:95], v[120:121], v[66:67] op_sel_hi:[1,0,1]
	v_pk_fma_f32 v[60:61], v[92:93], v[120:121], v[60:61] op_sel:[0,1,0]
	v_pk_fma_f32 v[62:63], v[94:95], v[120:121], v[62:63] op_sel:[0,1,0]
	v_pk_fma_f32 v[56:57], v[92:93], v[122:123], v[56:57] op_sel_hi:[1,0,1]
	v_pk_fma_f32 v[58:59], v[94:95], v[122:123], v[58:59] op_sel_hi:[1,0,1]
	v_pk_fma_f32 v[52:53], v[92:93], v[122:123], v[52:53] op_sel:[0,1,0]
	v_pk_fma_f32 v[54:55], v[94:95], v[122:123], v[54:55] op_sel:[0,1,0]
	v_pk_fma_f32 v[48:49], v[92:93], v[124:125], v[48:49] op_sel_hi:[1,0,1]
	v_pk_fma_f32 v[50:51], v[94:95], v[124:125], v[50:51] op_sel_hi:[1,0,1]
	v_pk_fma_f32 v[40:41], v[92:93], v[124:125], v[40:41] op_sel:[0,1,0]
	v_pk_fma_f32 v[42:43], v[94:95], v[124:125], v[42:43] op_sel:[0,1,0]
	v_pk_fma_f32 v[36:37], v[92:93], v[126:127], v[36:37] op_sel_hi:[1,0,1]
	v_pk_fma_f32 v[38:39], v[94:95], v[126:127], v[38:39] op_sel_hi:[1,0,1]
	v_pk_fma_f32 v[44:45], v[92:93], v[126:127], v[44:45] op_sel:[0,1,0]
	v_pk_fma_f32 v[46:47], v[94:95], v[126:127], v[46:47] op_sel:[0,1,0]
	ds_read_b128 v[120:123], v118 offset:1536
	ds_read_b128 v[124:127], v118 offset:1552
	s_waitcnt lgkmcnt(2)
; #define LAS __attribute__((address_space(3)))
; template <int TY> __device__ __forceinline__ void sample_item(const Params& p, ldsp lds, int item) {
;     ...
; #pragma unroll 8
;     for (int d = dg; d < DK; d += NG) { const f32x4 s0 = __builtin_nontemporal_load((const f32x4*)(S0 + (size_t)d * DV + e4 * 4));
;         const f32x4 qa = *(const LAS f32x4*)(QK + d * 16), qb = *(const LAS f32x4*)(QK + d * 16 + 4), ka = *(const LAS f32x4*)(QK + d * 16 + 8), kb = *(const LAS f32x4*)(QK + d * 16 + 12);
;         const float dc = DECs[d];
;         o[0] += s0 * qa[0]; o[1] += s0 * qa[1]; o[2] += s0 * qa[2]; o[3] += s0 * qa[3]; o[4] += s0 * qb[0]; o[5] += s0 * qb[1]; o[6] += s0 * qb[2]; o[7] += s0 * qb[3];
;         f32x4 sn = s0 * dc; sn += v[0] * ka[0]; sn += v[1] * ka[1]; sn += v[2] * ka[2]; sn += v[3] * ka[3]; sn += v[4] * kb[0]; sn += v[5] * kb[1]; sn += v[6] * kb[2]; sn += v[7] * kb[3];
;         __builtin_nontemporal_store(sn, (f32x4*)(S1 + (size_t)d * DV + e4 * 4)); }
	v_pk_mul_f32 v[92:93], v[92:93], v[136:137] op_sel_hi:[1,0]
	v_pk_mul_f32 v[94:95], v[94:95], v[136:137] op_sel_hi:[1,0]
	v_pk_fma_f32 v[92:93], v[0:1], v[128:129], v[92:93] op_sel_hi:[1,0,1]
	v_pk_fma_f32 v[94:95], v[2:3], v[128:129], v[94:95] op_sel_hi:[1,0,1]
	v_pk_fma_f32 v[92:93], v[4:5], v[128:129], v[92:93] op_sel:[0,1,0]
	v_pk_fma_f32 v[94:95], v[6:7], v[128:129], v[94:95] op_sel:[0,1,0]
	v_pk_fma_f32 v[92:93], v[8:9], v[130:131], v[92:93] op_sel_hi:[1,0,1]
	v_pk_fma_f32 v[94:95], v[10:11], v[130:131], v[94:95] op_sel_hi:[1,0,1]
	v_pk_fma_f32 v[92:93], v[12:13], v[130:131], v[92:93] op_sel:[0,1,0]
	v_pk_fma_f32 v[94:95], v[14:15], v[130:131], v[94:95] op_sel:[0,1,0]
	v_pk_fma_f32 v[92:93], v[20:21], v[132:133], v[92:93] op_sel_hi:[1,0,1]
	v_pk_fma_f32 v[94:95], v[22:23], v[132:133], v[94:95] op_sel_hi:[1,0,1]
	v_pk_fma_f32 v[92:93], v[24:25], v[132:133], v[92:93] op_sel:[0,1,0]
	v_pk_fma_f32 v[94:95], v[26:27], v[132:133], v[94:95] op_sel:[0,1,0]
	v_pk_fma_f32 v[92:93], v[28:29], v[134:135], v[92:93] op_sel_hi:[1,0,1]
	v_pk_fma_f32 v[94:95], v[30:31], v[134:135], v[94:95] op_sel_hi:[1,0,1]
	v_pk_fma_f32 v[92:93], v[32:33], v[134:135], v[92:93] op_sel:[0,1,0]
	v_pk_fma_f32 v[94:95], v[34:35], v[134:135], v[94:95] op_sel:[0,1,0]
	global_store_dwordx4 v109, v[92:95], s[14:15] nt
	ds_read_b128 v[128:131], v118 offset:1568
	ds_read_b128 v[132:135], v118 offset:1584
	ds_read_b32 v136, v16 offset:96
	s_waitcnt vmcnt(8) lgkmcnt(3)
	v_pk_fma_f32 v[64:65], v[96:97], v[120:121], v[64:65] op_sel_hi:[1,0,1]
	v_pk_fma_f32 v[66:67], v[98:99], v[120:121], v[66:67] op_sel_hi:[1,0,1]
	v_pk_fma_f32 v[60:61], v[96:97], v[120:121], v[60:61] op_sel:[0,1,0]
	v_pk_fma_f32 v[62:63], v[98:99], v[120:121], v[62:63] op_sel:[0,1,0]
	v_pk_fma_f32 v[56:57], v[96:97], v[122:123], v[56:57] op_sel_hi:[1,0,1]
	v_pk_fma_f32 v[58:59], v[98:99], v[122:123], v[58:59] op_sel_hi:[1,0,1]
	v_pk_fma_f32 v[52:53], v[96:97], v[122:123], v[52:53] op_sel:[0,1,0]
	v_pk_fma_f32 v[54:55], v[98:99], v[122:123], v[54:55] op_sel:[0,1,0]
	v_pk_fma_f32 v[48:49], v[96:97], v[124:125], v[48:49] op_sel_hi:[1,0,1]
	v_pk_fma_f32 v[50:51], v[98:99], v[124:125], v[50:51] op_sel_hi:[1,0,1]
	v_pk_fma_f32 v[40:41], v[96:97], v[124:125], v[40:41] op_sel:[0,1,0]
	v_pk_fma_f32 v[42:43], v[98:99], v[124:125], v[42:43] op_sel:[0,1,0]
	v_pk_fma_f32 v[36:37], v[96:97], v[126:127], v[36:37] op_sel_hi:[1,0,1]
	v_pk_fma_f32 v[38:39], v[98:99], v[126:127], v[38:39] op_sel_hi:[1,0,1]
	v_pk_fma_f32 v[44:45], v[96:97], v[126:127], v[44:45] op_sel:[0,1,0]
	v_pk_fma_f32 v[46:47], v[98:99], v[126:127], v[46:47] op_sel:[0,1,0]
	ds_read_b128 v[120:123], v118 offset:1792
	ds_read_b128 v[124:127], v118 offset:1808
	s_waitcnt lgkmcnt(2)
	v_pk_mul_f32 v[96:97], v[96:97], v[136:137] op_sel_hi:[1,0]
	v_pk_mul_f32 v[98:99], v[98:99], v[136:137] op_sel_hi:[1,0]
	v_pk_fma_f32 v[96:97], v[0:1], v[128:129], v[96:97] op_sel_hi:[1,0,1]
	v_pk_fma_f32 v[98:99], v[2:3], v[128:129], v[98:99] op_sel_hi:[1,0,1]
	v_pk_fma_f32 v[96:97], v[4:5], v[128:129], v[96:97] op_sel:[0,1,0]
	v_pk_fma_f32 v[98:99], v[6:7], v[128:129], v[98:99] op_sel:[0,1,0]
	v_pk_fma_f32 v[96:97], v[8:9], v[130:131], v[96:97] op_sel_hi:[1,0,1]
	v_pk_fma_f32 v[98:99], v[10:11], v[130:131], v[98:99] op_sel_hi:[1,0,1]
	v_pk_fma_f32 v[96:97], v[12:13], v[130:131], v[96:97] op_sel:[0,1,0]
	v_pk_fma_f32 v[98:99], v[14:15], v[130:131], v[98:99] op_sel:[0,1,0]
	v_pk_fma_f32 v[96:97], v[20:21], v[132:133], v[96:97] op_sel_hi:[1,0,1]
	v_pk_fma_f32 v[98:99], v[22:23], v[132:133], v[98:99] op_sel_hi:[1,0,1]
	v_pk_fma_f32 v[96:97], v[24:25], v[132:133], v[96:97] op_sel:[0,1,0]
	v_pk_fma_f32 v[98:99], v[26:27], v[132:133], v[98:99] op_sel:[0,1,0]
	v_pk_fma_f32 v[96:97], v[28:29], v[134:135], v[96:97] op_sel_hi:[1,0,1]
	v_pk_fma_f32 v[98:99], v[30:31], v[134:135], v[98:99] op_sel_hi:[1,0,1]
	v_pk_fma_f32 v[96:97], v[32:33], v[134:135], v[96:97] op_sel:[0,1,0]
	v_pk_fma_f32 v[98:99], v[34:35], v[134:135], v[98:99] op_sel:[0,1,0]
	global_store_dwordx4 v110, v[96:99], s[14:15] nt
	ds_read_b128 v[128:131], v118 offset:1824
	ds_read_b128 v[132:135], v118 offset:1840
	ds_read_b32 v136, v16 offset:112
	s_waitcnt vmcnt(7) lgkmcnt(3)
	v_pk_fma_f32 v[64:65], v[100:101], v[120:121], v[64:65] op_sel_hi:[1,0,1]
	v_pk_fma_f32 v[66:67], v[102:103], v[120:121], v[66:67] op_sel_hi:[1,0,1]
	v_pk_fma_f32 v[60:61], v[100:101], v[120:121], v[60:61] op_sel:[0,1,0]
	v_pk_fma_f32 v[62:63], v[102:103], v[120:121], v[62:63] op_sel:[0,1,0]
	v_pk_fma_f32 v[56:57], v[100:101], v[122:123], v[56:57] op_sel_hi:[1,0,1]
	v_pk_fma_f32 v[58:59], v[102:103], v[122:123], v[58:59] op_sel_hi:[1,0,1]
	v_pk_fma_f32 v[52:53], v[100:101], v[122:123], v[52:53] op_sel:[0,1,0]
	v_pk_fma_f32 v[54:55], v[102:103], v[122:123], v[54:55] op_sel:[0,1,0]
	v_pk_fma_f32 v[48:49], v[100:101], v[124:125], v[48:49] op_sel_hi:[1,0,1]
	v_pk_fma_f32 v[50:51], v[102:103], v[124:125], v[50:51] op_sel_hi:[1,0,1]
	v_pk_fma_f32 v[40:41], v[100:101], v[124:125], v[40:41] op_sel:[0,1,0]
	v_pk_fma_f32 v[42:43], v[102:103], v[124:125], v[42:43] op_sel:[0,1,0]
	v_pk_fma_f32 v[36:37], v[100:101], v[126:127], v[36:37] op_sel_hi:[1,0,1]
	v_pk_fma_f32 v[38:39], v[102:103], v[126:127], v[38:39] op_sel_hi:[1,0,1]
	v_pk_fma_f32 v[44:45], v[100:101], v[126:127], v[44:45] op_sel:[0,1,0]
	v_pk_fma_f32 v[46:47], v[102:103], v[126:127], v[46:47] op_sel:[0,1,0]
	s_waitcnt lgkmcnt(0)
	v_pk_mul_f32 v[100:101], v[100:101], v[136:137] op_sel_hi:[1,0]
	v_pk_mul_f32 v[102:103], v[102:103], v[136:137] op_sel_hi:[1,0]
	v_pk_fma_f32 v[100:101], v[0:1], v[128:129], v[100:101] op_sel_hi:[1,0,1]
	v_pk_fma_f32 v[102:103], v[2:3], v[128:129], v[102:103] op_sel_hi:[1,0,1]
	v_pk_fma_f32 v[100:101], v[4:5], v[128:129], v[100:101] op_sel:[0,1,0]
	v_pk_fma_f32 v[102:103], v[6:7], v[128:129], v[102:103] op_sel:[0,1,0]
	v_pk_fma_f32 v[100:101], v[8:9], v[130:131], v[100:101] op_sel_hi:[1,0,1]
	v_pk_fma_f32 v[102:103], v[10:11], v[130:131], v[102:103] op_sel_hi:[1,0,1]
	v_pk_fma_f32 v[100:101], v[12:13], v[130:131], v[100:101] op_sel:[0,1,0]
	v_pk_fma_f32 v[102:103], v[14:15], v[130:131], v[102:103] op_sel:[0,1,0]
	v_pk_fma_f32 v[100:101], v[20:21], v[132:133], v[100:101] op_sel_hi:[1,0,1]
	v_pk_fma_f32 v[102:103], v[22:23], v[132:133], v[102:103] op_sel_hi:[1,0,1]
	v_pk_fma_f32 v[100:101], v[24:25], v[132:133], v[100:101] op_sel:[0,1,0]
	v_pk_fma_f32 v[102:103], v[26:27], v[132:133], v[102:103] op_sel:[0,1,0]
	v_pk_fma_f32 v[100:101], v[28:29], v[134:135], v[100:101] op_sel_hi:[1,0,1]
	v_pk_fma_f32 v[102:103], v[30:31], v[134:135], v[102:103] op_sel_hi:[1,0,1]
	v_pk_fma_f32 v[100:101], v[32:33], v[134:135], v[100:101] op_sel:[0,1,0]
	v_pk_fma_f32 v[102:103], v[34:35], v[134:135], v[102:103] op_sel:[0,1,0]
	global_store_dwordx4 v111, v[100:103], s[14:15] nt
	s_or_b64 exec, exec, s[10:11]

; __device__ __forceinline__ unsigned pk2(float lo, float hi) { return pg8::cvt_pk_bf16(lo, hi); }
; template <int DK, int DV, int NC, bool RET> __device__ __forceinline__ void scan_states(const bf16_t* HL, const float* DEC, bf16_t* ST, float* outp) {
;     ...
;     for (int it = 0; it < niter; ++it) {
;         int dq, e, bh;
;         if (xm) { const int j = lt + 16384 * it; if (j >= 4 * PB) break; bh = (blockIdx.x & 7) + 8 * (j / PB); const int rem = j % PB; e = rem / DQ; dq = rem % DQ; }
;         else { const int idx = gtid + it * GT; if (idx >= total) break; dq = idx % DQ; e = (idx / DQ) % DV; bh = idx / (DQ * DV); }
;         f32x4 S = (f32x4){0.f, 0.f, 0.f, 0.f}; float c_st = 1.f, c_dec = 1.f, c_h = 1.f;
;         if (RET) { const float l2g = __log2f(1.0f - exp2f(-5.0f - (float)(bh & 3))); c_st = exp2f(129.f * l2g); c_dec = exp2f(256.f * l2g); c_h = exp2f(127.f * l2g); }
; #pragma unroll 8
;         for (int c = 0; c < NC; ++c) { const size_t base = (((size_t)bh * NC + c) * DV + e) * DK + dq * 4;
;             if (c != 0) { u32x2 w; w.x = pk2(S[0] * c_st, S[1] * c_st); w.y = pk2(S[2] * c_st, S[3] * c_st); *(u32x2*)(ST + base) = w; }
;             const u32x2 hw = __builtin_nontemporal_load((const u32x2*)(HL + base)); const f32x4 hl = (f32x4){bf2f(hw.x & 0xffffu), bf2f(hw.x >> 16), bf2f(hw.y & 0xffffu), bf2f(hw.y >> 16)};
;             f32x4 dec; if (RET) dec = (f32x4){c_dec, c_dec, c_dec, c_dec}; else dec = *(const f32x4*)(DEC + ((size_t)bh * NC + c) * DK + dq * 4);
;             S = dec * S + hl * c_h; }
; #pragma unroll
;         for (int j = 0; j < 4; ++j) outp[((size_t)bh * DK + dq * 4 + j) * DV + e] = S[j];
.LBB0_1157:
	v_ashrrev_i32_e32 v3, 31, v2
	v_ashrrev_i32_e32 v1, 31, v0
	v_lshlrev_b64 v[8:9], 19, v[2:3]
	v_lshlrev_b64 v[12:13], 7, v[0:1]
	v_lshlrev_b64 v[10:11], 6, v[0:1]
	v_lshlrev_b32_e32 v4, 2, v21
	v_lshl_add_u64 v[8:9], v[8:9], 0, v[12:13]
	v_lshlrev_b64 v[12:13], 18, v[2:3]
	v_ashrrev_i32_e32 v5, 31, v4
	v_lshl_add_u64 v[10:11], v[12:13], 0, v[10:11]
	v_lshlrev_b64 v[6:7], 13, v[2:3]
	v_lshl_add_u64 v[10:11], v[10:11], 0, v[4:5]
	v_mov_b32_e32 v14, 0
	v_lshl_add_u64 v[6:7], v[4:5], 2, v[6:7]
	v_lshl_add_u64 v[8:9], v[4:5], 1, v[8:9]
	v_lshlrev_b64 v[10:11], 1, v[10:11]
	v_mov_b32_e32 v15, v14
	v_mov_b32_e32 v18, v14
	v_mov_b32_e32 v19, v14
	s_add_u32 s12, s68, 0x27821000
	s_addc_u32 s13, s69, 0
	v_lshl_add_u64 v[114:115], s[12:13], 0, v[10:11]
	s_add_u32 s12, s68, 0x2f921000
	s_addc_u32 s13, s69, 0
	v_lshl_add_u64 v[116:117], s[12:13], 0, v[10:11]
	s_add_u32 s12, s68, 0x2f821000
	s_addc_u32 s13, s69, 0
	v_lshl_add_u64 v[118:119], s[12:13], 0, v[6:7]
	s_mov_b64 s[16:17], 0x4000
	s_mov_b32 s12, 0
.Lscan_gla:
	global_load_dwordx2 v[66:67], v[114:115], off nt
	global_load_dwordx4 v[82:85], v[118:119], off
	v_lshl_add_u64 v[120:121], v[114:115], 0, s[16:17]
	global_load_dwordx2 v[68:69], v[120:121], off nt
	global_load_dwordx4 v[86:89], v[118:119], off offset:256
	v_lshl_add_u64 v[120:121], v[120:121], 0, s[16:17]
	global_load_dwordx2 v[70:71], v[120:121], off nt
	global_load_dwordx4 v[90:93], v[118:119], off offset:512
	v_lshl_add_u64 v[120:121], v[120:121], 0, s[16:17]
	global_load_dwordx2 v[72:73], v[120:121], off nt
	global_load_dwordx4 v[94:97], v[118:119], off offset:768
	v_lshl_add_u64 v[120:121], v[120:121], 0, s[16:17]
	global_load_dwordx2 v[74:75], v[120:121], off nt
	global_load_dwordx4 v[98:101], v[118:119], off offset:1024
	v_lshl_add_u64 v[120:121], v[120:121], 0, s[16:17]
	global_load_dwordx2 v[76:77], v[120:121], off nt
	global_load_dwordx4 v[102:105], v[118:119], off offset:1280
	v_lshl_add_u64 v[120:121], v[120:121], 0, s[16:17]
	global_load_dwordx2 v[78:79], v[120:121], off nt
	global_load_dwordx4 v[106:109], v[118:119], off offset:1536
	v_lshl_add_u64 v[120:121], v[120:121], 0, s[16:17]
	global_load_dwordx2 v[80:81], v[120:121], off nt
	global_load_dwordx4 v[110:113], v[118:119], off offset:1792
	v_lshl_add_u64 v[114:115], v[120:121], 0, s[16:17]
	v_add_co_u32_e32 v118, vcc, 0x800, v118
	s_nop 1
	v_addc_co_u32_e32 v119, vcc, 0, v119, vcc
	s_cmp_eq_u32 s12, 0
	s_cbranch_scc1 .Lscan_gla_nost
	v_cvt_pk_bf16_f32 v22, v14, v15
	v_cvt_pk_bf16_f32 v23, v18, v19
	global_store_dwordx2 v[116:117], v[22:23], off
.Lscan_gla_nost:
	v_lshl_add_u64 v[116:117], v[116:117], 0, s[16:17]
	s_waitcnt vmcnt(14)
	v_lshlrev_b32_e32 v26, 16, v66
	v_and_b32_e32 v27, 0xffff0000, v66
	v_lshlrev_b32_e32 v28, 16, v67
	v_and_b32_e32 v29, 0xffff0000, v67
	v_pk_fma_f32 v[14:15], v[14:15], v[82:83], v[26:27]
	v_pk_fma_f32 v[18:19], v[18:19], v[84:85], v[28:29]
	v_cvt_pk_bf16_f32 v24, v14, v15
	v_cvt_pk_bf16_f32 v25, v18, v19
	global_store_dwordx2 v[116:117], v[24:25], off
	v_lshl_add_u64 v[116:117], v[116:117], 0, s[16:17]
	s_waitcnt vmcnt(13)
	v_lshlrev_b32_e32 v26, 16, v68
	v_and_b32_e32 v27, 0xffff0000, v68
	v_lshlrev_b32_e32 v28, 16, v69
	v_and_b32_e32 v29, 0xffff0000, v69
	v_pk_fma_f32 v[14:15], v[14:15], v[86:87], v[26:27]
	v_pk_fma_f32 v[18:19], v[18:19], v[88:89], v[28:29]
	v_cvt_pk_bf16_f32 v22, v14, v15
	v_cvt_pk_bf16_f32 v23, v18, v19
	global_store_dwordx2 v[116:117], v[22:23], off
	v_lshl_add_u64 v[116:117], v[116:117], 0, s[16:17]
	s_waitcnt vmcnt(12)
	v_lshlrev_b32_e32 v26, 16, v70
	v_and_b32_e32 v27, 0xffff0000, v70
	v_lshlrev_b32_e32 v28, 16, v71
	v_and_b32_e32 v29, 0xffff0000, v71
	v_pk_fma_f32 v[14:15], v[14:15], v[90:91], v[26:27]
	v_pk_fma_f32 v[18:19], v[18:19], v[92:93], v[28:29]
	v_cvt_pk_bf16_f32 v24, v14, v15
	v_cvt_pk_bf16_f32 v25, v18, v19
	global_store_dwordx2 v[116:117], v[24:25], off
	v_lshl_add_u64 v[116:117], v[116:117], 0, s[16:17]
	s_waitcnt vmcnt(11)
	v_lshlrev_b32_e32 v26, 16, v72
	v_and_b32_e32 v27, 0xffff0000, v72
	v_lshlrev_b32_e32 v28, 16, v73
	v_and_b32_e32 v29, 0xffff0000, v73
	v_pk_fma_f32 v[14:15], v[14:15], v[94:95], v[26:27]
	v_pk_fma_f32 v[18:19], v[18:19], v[96:97], v[28:29]
	v_cvt_pk_bf16_f32 v22, v14, v15
	v_cvt_pk_bf16_f32 v23, v18, v19
	global_store_dwordx2 v[116:117], v[22:23], off
	v_lshl_add_u64 v[116:117], v[116:117], 0, s[16:17]
	s_waitcnt vmcnt(10)
	v_lshlrev_b32_e32 v26, 16, v74
	v_and_b32_e32 v27, 0xffff0000, v74
	v_lshlrev_b32_e32 v28, 16, v75
	v_and_b32_e32 v29, 0xffff0000, v75
	v_pk_fma_f32 v[14:15], v[14:15], v[98:99], v[26:27]
	v_pk_fma_f32 v[18:19], v[18:19], v[100:101], v[28:29]
	v_cvt_pk_bf16_f32 v24, v14, v15
	v_cvt_pk_bf16_f32 v25, v18, v19
	global_store_dwordx2 v[116:117], v[24:25], off
	v_lshl_add_u64 v[116:117], v[116:117], 0, s[16:17]
	s_waitcnt vmcnt(9)
	v_lshlrev_b32_e32 v26, 16, v76
	v_and_b32_e32 v27, 0xffff0000, v76
	v_lshlrev_b32_e32 v28, 16, v77
	v_and_b32_e32 v29, 0xffff0000, v77
	v_pk_fma_f32 v[14:15], v[14:15], v[102:103], v[26:27]
	v_pk_fma_f32 v[18:19], v[18:19], v[104:105], v[28:29]
	v_cvt_pk_bf16_f32 v22, v14, v15
	v_cvt_pk_bf16_f32 v23, v18, v19
	global_store_dwordx2 v[116:117], v[22:23], off
	v_lshl_add_u64 v[116:117], v[116:117], 0, s[16:17]
	s_waitcnt vmcnt(8)
	v_lshlrev_b32_e32 v26, 16, v78
	v_and_b32_e32 v27, 0xffff0000, v78
	v_lshlrev_b32_e32 v28, 16, v79
	v_and_b32_e32 v29, 0xffff0000, v79
	v_pk_fma_f32 v[14:15], v[14:15], v[106:107], v[26:27]
	v_pk_fma_f32 v[18:19], v[18:19], v[108:109], v[28:29]
	v_cvt_pk_bf16_f32 v24, v14, v15
	v_cvt_pk_bf16_f32 v25, v18, v19
	global_store_dwordx2 v[116:117], v[24:25], off
	v_lshl_add_u64 v[116:117], v[116:117], 0, s[16:17]
	s_waitcnt vmcnt(7)
	v_lshlrev_b32_e32 v26, 16, v80
	v_and_b32_e32 v27, 0xffff0000, v80
	v_lshlrev_b32_e32 v28, 16, v81
	v_and_b32_e32 v29, 0xffff0000, v81
	v_pk_fma_f32 v[14:15], v[14:15], v[110:111], v[26:27]
	v_pk_fma_f32 v[18:19], v[18:19], v[112:113], v[28:29]
	s_add_i32 s12, s12, 1
	s_cmp_lt_u32 s12, 4
	s_cbranch_scc1 .Lscan_gla
	s_branch .LBB0_1146

; __device__ __forceinline__ unsigned pk2(float lo, float hi) { return pg8::cvt_pk_bf16(lo, hi); }
; template <int DK, int DV, int NC, bool RET> __device__ __forceinline__ void scan_states(const bf16_t* HL, const float* DEC, bf16_t* ST, float* outp) {
;     ...
;     for (int it = 0; it < niter; ++it) {
;         int dq, e, bh;
;         if (xm) { const int j = lt + 16384 * it; if (j >= 4 * PB) break; bh = (blockIdx.x & 7) + 8 * (j / PB); const int rem = j % PB; e = rem / DQ; dq = rem % DQ; }
;         else { const int idx = gtid + it * GT; if (idx >= total) break; dq = idx % DQ; e = (idx / DQ) % DV; bh = idx / (DQ * DV); }
;         f32x4 S = (f32x4){0.f, 0.f, 0.f, 0.f}; float c_st = 1.f, c_dec = 1.f, c_h = 1.f;
;         if (RET) { const float l2g = __log2f(1.0f - exp2f(-5.0f - (float)(bh & 3))); c_st = exp2f(129.f * l2g); c_dec = exp2f(256.f * l2g); c_h = exp2f(127.f * l2g); }
; #pragma unroll 8
;         for (int c = 0; c < NC; ++c) { const size_t base = (((size_t)bh * NC + c) * DV + e) * DK + dq * 4;
;             if (c != 0) { u32x2 w; w.x = pk2(S[0] * c_st, S[1] * c_st); w.y = pk2(S[2] * c_st, S[3] * c_st); *(u32x2*)(ST + base) = w; }
;             const u32x2 hw = __builtin_nontemporal_load((const u32x2*)(HL + base)); const f32x4 hl = (f32x4){bf2f(hw.x & 0xffffu), bf2f(hw.x >> 16), bf2f(hw.y & 0xffffu), bf2f(hw.y >> 16)};
;             f32x4 dec; if (RET) dec = (f32x4){c_dec, c_dec, c_dec, c_dec}; else dec = *(const f32x4*)(DEC + ((size_t)bh * NC + c) * DK + dq * 4);
;             S = dec * S + hl * c_h; }
; #pragma unroll
;         for (int j = 0; j < 4; ++j) outp[((size_t)bh * DK + dq * 4 + j) * DV + e] = S[j];
.LBB0_1177:
	v_ashrrev_i32_e32 v3, 31, v2
	v_ashrrev_i32_e32 v1, 31, v0
	v_lshlrev_b32_e32 v4, 2, v21
	v_lshlrev_b64 v[10:11], 19, v[2:3]
	v_lshlrev_b64 v[12:13], 7, v[0:1]
	v_ashrrev_i32_e32 v5, 31, v4
	v_lshlrev_b64 v[6:7], 20, v[2:3]
	v_lshlrev_b64 v[8:9], 8, v[0:1]
	v_lshl_add_u64 v[10:11], v[10:11], 0, v[12:13]
	v_lshl_add_u64 v[6:7], v[6:7], 0, v[8:9]
	v_lshlrev_b64 v[8:9], 14, v[2:3]
	v_lshl_add_u64 v[10:11], v[10:11], 0, v[4:5]
	v_mov_b32_e32 v14, 0
	v_lshl_add_u64 v[6:7], v[4:5], 1, v[6:7]
	v_lshl_add_u64 v[8:9], v[4:5], 2, v[8:9]
	v_lshlrev_b64 v[10:11], 1, v[10:11]
	v_mov_b32_e32 v15, v14
	v_mov_b32_e32 v18, v14
	v_mov_b32_e32 v19, v14
	s_add_u32 s12, s68, 0x29821000
	s_addc_u32 s13, s69, 0
	v_lshl_add_u64 v[114:115], s[12:13], 0, v[10:11]
	s_add_u32 s12, s68, 0x30921000
	s_addc_u32 s13, s69, 0
	v_lshl_add_u64 v[116:117], s[12:13], 0, v[10:11]
	s_add_u32 s12, s68, 0x2f861000
	s_addc_u32 s13, s69, 0
	v_lshl_add_u64 v[118:119], s[12:13], 0, v[8:9]
	s_mov_b64 s[16:17], 0x8000
	s_mov_b32 s12, 0
.Lscan_hgrn:
	global_load_dwordx2 v[66:67], v[114:115], off nt
	global_load_dwordx4 v[82:85], v[118:119], off
	v_lshl_add_u64 v[120:121], v[114:115], 0, s[16:17]
	global_load_dwordx2 v[68:69], v[120:121], off nt
	global_load_dwordx4 v[86:89], v[118:119], off offset:512
	v_lshl_add_u64 v[120:121], v[120:121], 0, s[16:17]
	global_load_dwordx2 v[70:71], v[120:121], off nt
	global_load_dwordx4 v[90:93], v[118:119], off offset:1024
	v_lshl_add_u64 v[120:121], v[120:121], 0, s[16:17]
	global_load_dwordx2 v[72:73], v[120:121], off nt
	global_load_dwordx4 v[94:97], v[118:119], off offset:1536
	v_lshl_add_u64 v[120:121], v[120:121], 0, s[16:17]
	global_load_dwordx2 v[74:75], v[120:121], off nt
	global_load_dwordx4 v[98:101], v[118:119], off offset:2048
	v_lshl_add_u64 v[120:121], v[120:121], 0, s[16:17]
	global_load_dwordx2 v[76:77], v[120:121], off nt
	global_load_dwordx4 v[102:105], v[118:119], off offset:2560
	v_lshl_add_u64 v[120:121], v[120:121], 0, s[16:17]
	global_load_dwordx2 v[78:79], v[120:121], off nt
	global_load_dwordx4 v[106:109], v[118:119], off offset:3072
	v_lshl_add_u64 v[120:121], v[120:121], 0, s[16:17]
	global_load_dwordx2 v[80:81], v[120:121], off nt
	global_load_dwordx4 v[110:113], v[118:119], off offset:3584
	v_lshl_add_u64 v[114:115], v[120:121], 0, s[16:17]
	v_add_co_u32_e32 v118, vcc, 0x1000, v118
	s_nop 1
	v_addc_co_u32_e32 v119, vcc, 0, v119, vcc
	s_cmp_eq_u32 s12, 0
	s_cbranch_scc1 .Lscan_hgrn_nost
	v_cvt_pk_bf16_f32 v22, v14, v15
	v_cvt_pk_bf16_f32 v23, v18, v19
	global_store_dwordx2 v[116:117], v[22:23], off

; __device__ __forceinline__ unsigned pk2(float lo, float hi) { return pg8::cvt_pk_bf16(lo, hi); }
; __device__ __forceinline__ float wave_sum(float v) {
; #pragma unroll
;     for (int o = 1; o < 64; o <<= 1) v += __shfl_xor(v, o);
;     return v;
; }
; __device__ __forceinline__ void row_pass(const Params& p, int mode, float coef, const float* nw, int nsplit) {
;     ...
;             float q = 0.f;
; #pragma unroll
;             for (int j = 0; j < 4; ++j) q += (fv[j][0] * fv[j][0] + fv[j][1] * fv[j][1]) + (fv[j][2] * fv[j][2] + fv[j][3] * fv[j][3]);
;             q = wave_sum(q);
;             const float rstd = rsqrtf(q * (1.0f / D) + EPS) * coef; const f32x4* W4 = (const f32x4*)nw;
; #pragma unroll
;             for (int j = 0; j < 4; ++j) { const f32x4 xv = (f32x4){bf2f(xw[j].x & 0xffffu), bf2f(xw[j].x >> 16), bf2f(xw[j].y & 0xffffu), bf2f(xw[j].y >> 16)};
;                 v[j] = xv + fv[j] * W4[64 * j + lane] * rstd; }
;         }
;         if (mode == 2) { f32x4* X4 = (f32x4*)(p.out + (size_t)r * D);
; #pragma unroll
;             for (int j = 0; j < 4; ++j) X4[64 * j + lane] = v[j];
;         } else {
;             float s = 0.f;
; #pragma unroll
;             for (int j = 0; j < 4; ++j) s += (v[j][0] * v[j][0] + v[j][1] * v[j][1]) + (v[j][2] * v[j][2] + v[j][3] * v[j][3]);
;             s = wave_sum(s);
; #pragma unroll
;             for (int j = 0; j < 4; ++j) { u32x2 w; w.x = pk2(v[j][0], v[j][1]); w.y = pk2(v[j][2], v[j][3]); B2[64 * j + lane] = w; }
;             if (lane == 0) RS[r] = rsqrtf(s * (1.0f / D) + EPS);
.LBB0_1460:
	s_or_b64 exec, exec, s[14:15]
	v_pk_mul_f32 v[52:53], v[40:41], v[40:41]
	v_pk_mul_f32 v[54:55], v[38:39], v[38:39]
	v_pk_mul_f32 v[44:45], v[36:37], v[36:37]
	v_pk_mov_b32 v[56:57], v[54:55], v[52:53] op_sel:[1,0]
	v_mov_b32_e32 v55, v53
	v_pk_add_f32 v[52:53], v[56:57], v[54:55]
	global_load_dwordx4 v[56:59], v[6:7], off
	v_pk_mul_f32 v[50:51], v[34:35], v[34:35]
	v_mul_f32_e32 v16, v2, v2
	v_pk_mov_b32 v[54:55], v[50:51], v[44:45] op_sel:[1,0]
	v_mov_b32_e32 v51, v45
	v_pk_add_f32 v[44:45], v[54:55], v[50:51]
	v_pk_fma_f32 v[50:51], v[2:3], v[2:3], v[16:17] op_sel_hi:[1,1,0]
	v_mul_f32_e32 v16, v28, v28
	v_pk_add_f32 v[52:53], v[52:53], v[52:53] op_sel_hi:[0,1]
	v_pk_add_f32 v[44:45], v[44:45], v[44:45] op_sel_hi:[0,1]
	v_pk_fma_f32 v[54:55], v[28:29], v[28:29], v[16:17] op_sel_hi:[1,1,0]
	v_mul_f32_e32 v50, v24, v24
	v_mul_f32_e32 v54, v25, v25
	v_mul_f32_e32 v52, v26, v26
	v_mul_f32_e32 v44, v27, v27
	v_pk_add_f32 v[50:51], v[50:51], v[54:55]
	v_pk_add_f32 v[44:45], v[52:53], v[44:45]
	s_waitcnt vmcnt(0)
	v_pk_mul_f32 v[40:41], v[40:41], v[58:59]
	v_pk_add_f32 v[44:45], v[50:51], v[44:45]
	v_pk_mul_f32 v[56:57], v[38:39], v[56:57]
	v_add_f32_e32 v16, v44, v45
	v_and_b32_e32 v45, 0xffff0000, v42
	s_nop 0
	v_add_f32_dpp v16, v16, v16 quad_perm:[1,0,3,2] row_mask:0xf bank_mask:0xf
	s_nop 1
	v_add_f32_dpp v16, v16, v16 quad_perm:[2,3,0,1] row_mask:0xf bank_mask:0xf
	s_nop 1
	v_add_f32_dpp v16, v16, v16 row_ror:4 row_mask:0xf bank_mask:0xf
	s_nop 1
	v_add_f32_dpp v16, v16, v16 row_ror:8 row_mask:0xf bank_mask:0xf
	s_nop 1
	v_add_f32_dpp v16, v16, v16 row_bcast:15 row_mask:0xa bank_mask:0xf
	s_nop 1
	v_add_f32_dpp v16, v16, v16 row_bcast:31 row_mask:0xc bank_mask:0xf
	s_nop 0
	v_readlane_b32 s16, v16, 63
	v_mov_b32_e32 v44, 0x358637bd
	s_nop 0
	v_mov_b32_e32 v16, s16
	v_fmamk_f32 v16, v16, 0x3a800000, v44
	v_cmp_gt_f32_e32 vcc, s33, v16
	v_mul_f32_e32 v44, 0x4b800000, v16
	s_nop 0
	v_cndmask_b32_e32 v16, v16, v44, vcc
	v_rsq_f32_e32 v16, v16
	s_nop 0
	v_mul_f32_e32 v44, 0x45800000, v16
	v_cndmask_b32_e32 v16, v16, v44, vcc
	v_lshlrev_b32_e32 v44, 16, v42
	v_lshlrev_b32_e32 v42, 16, v43
	v_and_b32_e32 v43, 0xffff0000, v43
	v_pk_fma_f32 v[38:39], v[40:41], v[16:17], v[42:43] op_sel_hi:[1,0,1]
	v_pk_fma_f32 v[40:41], v[56:57], v[16:17], v[44:45] op_sel_hi:[1,0,1]
	global_load_dwordx4 v[42:45], v[8:9], off
	v_lshlrev_b32_e32 v56, 16, v32
	v_and_b32_e32 v57, 0xffff0000, v32
	v_lshlrev_b32_e32 v32, 16, v33
	v_and_b32_e32 v33, 0xffff0000, v33
	s_waitcnt vmcnt(0)
	v_pk_mul_f32 v[36:37], v[36:37], v[44:45]
	v_pk_mul_f32 v[34:35], v[34:35], v[42:43]
	global_load_dwordx4 v[42:45], v[10:11], off
	v_pk_fma_f32 v[32:33], v[36:37], v[16:17], v[32:33] op_sel_hi:[1,0,1]
	v_lshlrev_b32_e32 v36, 16, v30
	v_and_b32_e32 v37, 0xffff0000, v30
	v_lshlrev_b32_e32 v30, 16, v31
	v_and_b32_e32 v31, 0xffff0000, v31
	v_pk_fma_f32 v[34:35], v[34:35], v[16:17], v[56:57] op_sel_hi:[1,0,1]
	s_waitcnt vmcnt(0)
	v_pk_mul_f32 v[28:29], v[28:29], v[44:45]
	v_pk_mul_f32 v[2:3], v[2:3], v[42:43]
	v_pk_fma_f32 v[28:29], v[28:29], v[16:17], v[30:31] op_sel_hi:[1,0,1]
	v_pk_fma_f32 v[30:31], v[2:3], v[16:17], v[36:37] op_sel_hi:[1,0,1]
	v_lshlrev_b32_e32 v36, 16, v0
	v_and_b32_e32 v37, 0xffff0000, v0
	v_lshlrev_b32_e32 v42, 16, v1
	v_and_b32_e32 v43, 0xffff0000, v1
	global_load_dwordx4 v[0:3], v[12:13], off
	s_waitcnt vmcnt(0)
	v_pk_mul_f32 v[0:1], v[24:25], v[0:1]
	s_nop 0
	v_pk_fma_f32 v[24:25], v[0:1], v[16:17], v[36:37] op_sel_hi:[1,0,1]
	v_mul_f32_e32 v0, v41, v41
	v_mul_f32_e32 v1, v39, v39
	v_pk_mul_f32 v[2:3], v[26:27], v[2:3]
	v_fmac_f32_e32 v0, v40, v40
	v_fmac_f32_e32 v1, v38, v38
	v_pk_fma_f32 v[2:3], v[2:3], v[16:17], v[42:43] op_sel_hi:[1,0,1]
	v_add_f32_e32 v0, v0, v1
	v_mul_f32_e32 v1, v35, v35
	v_mul_f32_e32 v16, v33, v33
	v_fmac_f32_e32 v1, v34, v34
	v_fmac_f32_e32 v16, v32, v32
	v_add_f32_e32 v1, v1, v16
	v_add_f32_e32 v0, v0, v1
	v_mul_f32_e32 v1, v31, v31
	v_mul_f32_e32 v16, v29, v29
	v_fmac_f32_e32 v1, v30, v30
	v_fmac_f32_e32 v16, v28, v28
	v_add_f32_e32 v1, v1, v16
	v_add_f32_e32 v0, v1, v0
	v_mul_f32_e32 v1, v25, v25
	v_mul_f32_e32 v16, v3, v3
	v_fmac_f32_e32 v1, v24, v24
	v_fmac_f32_e32 v16, v2, v2
	v_add_f32_e32 v1, v1, v16
	v_add_f32_e32 v0, v1, v0
	v_cvt_pk_bf16_f32 v26, v40, v41
	v_cvt_pk_bf16_f32 v27, v38, v39
	v_add_f32_dpp v0, v0, v0 quad_perm:[1,0,3,2] row_mask:0xf bank_mask:0xf
	global_store_dwordx2 v[22:23], v[26:27], off
	s_nop 0
	v_add_f32_dpp v0, v0, v0 quad_perm:[2,3,0,1] row_mask:0xf bank_mask:0xf
	v_cvt_pk_bf16_f32 v26, v34, v35
	v_cvt_pk_bf16_f32 v27, v32, v33
	v_add_f32_dpp v0, v0, v0 row_ror:4 row_mask:0xf bank_mask:0xf
	global_store_dwordx2 v[22:23], v[26:27], off offset:512
	s_nop 0
	v_add_f32_dpp v0, v0, v0 row_ror:8 row_mask:0xf bank_mask:0xf
	v_cvt_pk_bf16_f32 v26, v30, v31
	v_cvt_pk_bf16_f32 v27, v28, v29
	v_add_f32_dpp v0, v0, v0 row_bcast:15 row_mask:0xa bank_mask:0xf
	global_store_dwordx2 v[22:23], v[26:27], off offset:1024
	s_nop 0
	v_add_f32_dpp v0, v0, v0 row_bcast:31 row_mask:0xc bank_mask:0xf
	v_cvt_pk_bf16_f32 v24, v24, v25
	v_cvt_pk_bf16_f32 v25, v2, v3
	global_store_dwordx2 v[22:23], v[24:25], off offset:1536
	v_readlane_b32 s16, v0, 63
	s_and_saveexec_b64 s[14:15], s[10:11]
	s_cbranch_execz .LBB0_1441
	v_mov_b32_e32 v0, s16
	v_mov_b32_e32 v1, 0x358637bd
	v_fmamk_f32 v0, v0, 0x3a800000, v1
	v_mul_f32_e32 v1, 0x4b800000, v0
	v_cmp_gt_f32_e32 vcc, s33, v0
	v_readlane_b32 s16, v252, 39
	v_readlane_b32 s17, v252, 40
	v_cndmask_b32_e32 v0, v0, v1, vcc
	v_rsq_f32_e32 v0, v0
	s_nop 0
	v_mul_f32_e32 v1, 0x45800000, v0
	v_cndmask_b32_e32 v2, v0, v1, vcc
	v_lshl_add_u64 v[0:1], v[20:21], 2, s[16:17]
	global_store_dword v[0:1], v2, off
	s_branch .LBB0_1441
